# hand-written P5 epilogue for prompt tiles (DPP-fused conv FMAs, scalar control flow) + pool rewrite
# speedup vs baseline: 1.0161x; 1.0135x over previous
; #define GAS __attribute__((address_space(1)))
; __device__ __forceinline__ void pool_phase(Frame& F) {
;     const int total = (MT / 8) * 64;
;     for (int i = blockIdx.x * 512 + F.tid; i < total; i += F.G * 512) {
;         const int r0 = (i >> 6) * 8, c = (i & 63) * 4, g = c >> 6; const bool smp = r0 >= TP; const int rr = smp ? r0 - TP : r0; const int b = smp ? rr >> 3 : rr >> 11, t0 = smp ? 0 : rr & 2047;
;         const bf16* ub = F.U + (size_t)(r0 - t0) * 256 + c;
;         f32x4 x[23];
; #pragma unroll
;         for (int k = 0; k < 23; ++k) { const int tau = t0 - 15 + k;
;             if (tau >= 0) { const u32x2v hb = *(const GAS u32x2v*)(ub + (size_t)tau * 256);
;                 x[k] = (f32x4){__builtin_bit_cast(float, hb.x << 16), __builtin_bit_cast(float, hb.x & 0xffff0000u), __builtin_bit_cast(float, hb.y << 16), __builtin_bit_cast(float, hb.y & 0xffff0000u)}; } else if (smp) x[k] = *(const GAS f32x4*)(F.state_pool + ((size_t)b * 15 + 15 + tau) * 256 + c); else x[k] = (f32x4){0.f, 0.f, 0.f, 0.f}; }
.Lpool_loop:
	s_cmp_ge_u32 s40, 0x800
	s_cbranch_scc1 .Lpool_prompt_done
	s_lshl_b32 s42, s40, 3
	s_and_b32 s43, s40, 0xff
	s_lshl_b32 s43, s43, 3
	s_lshl_b32 s32, s42, 9
	s_add_u32 s60, s44, s32
	s_addc_u32 s61, s45, 0
	s_add_u32 s62, s60, 0x1000
	s_addc_u32 s63, s61, 0
	s_add_u32 s30, s60, 0x2000
	s_addc_u32 s31, s61, 0
	global_load_dwordx2 v[6:7], v244, s[60:61]
	global_load_dwordx2 v[10:11], v244, s[60:61] offset:512
	global_load_dwordx2 v[14:15], v244, s[60:61] offset:1024
	global_load_dwordx2 v[18:19], v244, s[60:61] offset:1536
	global_load_dwordx2 v[22:23], v244, s[60:61] offset:2048
	global_load_dwordx2 v[26:27], v244, s[60:61] offset:2560
	global_load_dwordx2 v[30:31], v244, s[60:61] offset:3072
	global_load_dwordx2 v[34:35], v244, s[60:61] offset:3584
	global_load_dwordx2 v[38:39], v244, s[62:63]
	global_load_dwordx2 v[42:43], v244, s[62:63] offset:512
	global_load_dwordx2 v[46:47], v244, s[62:63] offset:1024
	global_load_dwordx2 v[50:51], v244, s[62:63] offset:1536
	global_load_dwordx2 v[54:55], v244, s[62:63] offset:2048
	global_load_dwordx2 v[58:59], v244, s[62:63] offset:2560
	global_load_dwordx2 v[62:63], v244, s[62:63] offset:3072
	global_load_dwordx2 v[66:67], v244, s[62:63] offset:3584
	global_load_dwordx2 v[70:71], v244, s[30:31]
	global_load_dwordx2 v[74:75], v244, s[30:31] offset:512
	global_load_dwordx2 v[78:79], v244, s[30:31] offset:1024
	global_load_dwordx2 v[82:83], v244, s[30:31] offset:1536
	global_load_dwordx2 v[86:87], v244, s[30:31] offset:2048
	global_load_dwordx2 v[90:91], v244, s[30:31] offset:2560
	global_load_dwordx2 v[94:95], v244, s[30:31] offset:3072
	s_waitcnt vmcnt(0)
	v_lshlrev_b32_e32 v4, 16, v6
	v_and_b32_e32 v5, s59, v6
	v_lshlrev_b32_e32 v6, 16, v7
	v_and_b32_e32 v7, s59, v7
	v_lshlrev_b32_e32 v8, 16, v10
	v_and_b32_e32 v9, s59, v10
	v_lshlrev_b32_e32 v10, 16, v11
	v_and_b32_e32 v11, s59, v11
	v_lshlrev_b32_e32 v12, 16, v14
	v_and_b32_e32 v13, s59, v14
	v_lshlrev_b32_e32 v14, 16, v15
	v_and_b32_e32 v15, s59, v15
	v_lshlrev_b32_e32 v16, 16, v18
	v_and_b32_e32 v17, s59, v18
	v_lshlrev_b32_e32 v18, 16, v19
	v_and_b32_e32 v19, s59, v19
	v_lshlrev_b32_e32 v20, 16, v22
	v_and_b32_e32 v21, s59, v22
	v_lshlrev_b32_e32 v22, 16, v23
	v_and_b32_e32 v23, s59, v23
	v_lshlrev_b32_e32 v24, 16, v26
	v_and_b32_e32 v25, s59, v26
	v_lshlrev_b32_e32 v26, 16, v27
	v_and_b32_e32 v27, s59, v27
	v_lshlrev_b32_e32 v28, 16, v30
	v_and_b32_e32 v29, s59, v30
	v_lshlrev_b32_e32 v30, 16, v31
	v_and_b32_e32 v31, s59, v31
	v_lshlrev_b32_e32 v32, 16, v34
	v_and_b32_e32 v33, s59, v34
	v_lshlrev_b32_e32 v34, 16, v35
	v_and_b32_e32 v35, s59, v35
	v_lshlrev_b32_e32 v36, 16, v38
	v_and_b32_e32 v37, s59, v38
	v_lshlrev_b32_e32 v38, 16, v39
	v_and_b32_e32 v39, s59, v39
	v_lshlrev_b32_e32 v40, 16, v42
	v_and_b32_e32 v41, s59, v42
	v_lshlrev_b32_e32 v42, 16, v43
	v_and_b32_e32 v43, s59, v43
	v_lshlrev_b32_e32 v44, 16, v46
	v_and_b32_e32 v45, s59, v46
	v_lshlrev_b32_e32 v46, 16, v47
	v_and_b32_e32 v47, s59, v47
	v_lshlrev_b32_e32 v48, 16, v50
	v_and_b32_e32 v49, s59, v50
	v_lshlrev_b32_e32 v50, 16, v51
	v_and_b32_e32 v51, s59, v51
	v_lshlrev_b32_e32 v52, 16, v54
	v_and_b32_e32 v53, s59, v54
	v_lshlrev_b32_e32 v54, 16, v55
	v_and_b32_e32 v55, s59, v55
	v_lshlrev_b32_e32 v56, 16, v58
	v_and_b32_e32 v57, s59, v58
	v_lshlrev_b32_e32 v58, 16, v59
	v_and_b32_e32 v59, s59, v59
	v_lshlrev_b32_e32 v60, 16, v62
	v_and_b32_e32 v61, s59, v62
	v_lshlrev_b32_e32 v62, 16, v63
	v_and_b32_e32 v63, s59, v63
	s_cmp_ge_u32 s43, 16
	s_cbranch_scc1 .Lpool_common
	v_mov_b32_e32 v4, 0
	v_mov_b32_e32 v5, 0
	v_mov_b32_e32 v6, 0
	v_mov_b32_e32 v7, 0
	v_mov_b32_e32 v8, 0
	v_mov_b32_e32 v9, 0
	v_mov_b32_e32 v10, 0
	v_mov_b32_e32 v11, 0
	v_mov_b32_e32 v12, 0
	v_mov_b32_e32 v13, 0
	v_mov_b32_e32 v14, 0
	v_mov_b32_e32 v15, 0
	v_mov_b32_e32 v16, 0
	v_mov_b32_e32 v17, 0
	v_mov_b32_e32 v18, 0
	v_mov_b32_e32 v19, 0
	v_mov_b32_e32 v20, 0
	v_mov_b32_e32 v21, 0
	v_mov_b32_e32 v22, 0
	v_mov_b32_e32 v23, 0
	v_mov_b32_e32 v24, 0
	v_mov_b32_e32 v25, 0
	v_mov_b32_e32 v26, 0
	v_mov_b32_e32 v27, 0
	v_mov_b32_e32 v28, 0
	v_mov_b32_e32 v29, 0
	v_mov_b32_e32 v30, 0
	v_mov_b32_e32 v31, 0
	s_cmp_eq_u32 s43, 8
	s_cbranch_scc1 .Lpool_common
	v_mov_b32_e32 v32, 0
	v_mov_b32_e32 v33, 0
	v_mov_b32_e32 v34, 0
	v_mov_b32_e32 v35, 0
	v_mov_b32_e32 v36, 0
	v_mov_b32_e32 v37, 0
	v_mov_b32_e32 v38, 0
	v_mov_b32_e32 v39, 0
	v_mov_b32_e32 v40, 0
	v_mov_b32_e32 v41, 0
	v_mov_b32_e32 v42, 0
	v_mov_b32_e32 v43, 0
	v_mov_b32_e32 v44, 0
	v_mov_b32_e32 v45, 0
	v_mov_b32_e32 v46, 0
	v_mov_b32_e32 v47, 0
	v_mov_b32_e32 v48, 0
	v_mov_b32_e32 v49, 0
	v_mov_b32_e32 v50, 0
	v_mov_b32_e32 v51, 0
	v_mov_b32_e32 v52, 0
	v_mov_b32_e32 v53, 0
	v_mov_b32_e32 v54, 0
	v_mov_b32_e32 v55, 0
	v_mov_b32_e32 v56, 0
	v_mov_b32_e32 v57, 0
	v_mov_b32_e32 v58, 0
	v_mov_b32_e32 v59, 0
	v_mov_b32_e32 v60, 0
	v_mov_b32_e32 v61, 0
	v_mov_b32_e32 v62, 0
	v_mov_b32_e32 v63, 0
	s_branch .Lpool_common

; __device__ __forceinline__ void pool_phase(Frame& F) {
;     const int total = (MT / 8) * 64;
;     for (int i = blockIdx.x * 512 + F.tid; i < total; i += F.G * 512) {
;         const int r0 = (i >> 6) * 8, c = (i & 63) * 4, g = c >> 6; const bool smp = r0 >= TP; const int rr = smp ? r0 - TP : r0; const int b = smp ? rr >> 3 : rr >> 11, t0 = smp ? 0 : rr & 2047;
.Lpool_next:
	s_cmp_ge_u32 s40, 0x800
	s_cbranch_scc1 .Lpool_snext
	s_add_i32 s40, s40, s41
	s_branch .Lpool_loop
.Lpool_prompt_done:
	v_readfirstlane_b32 s32, v0
	s_nop 3
	s_cmp_ge_u32 s32, 64
	s_cbranch_scc1 .Lpool_done
	s_add_i32 s40, s88, 0x800
.Lpool_sloop:
	s_cmp_ge_u32 s40, 0x880
	s_cbranch_scc1 .Lpool_done
	s_lshl_b32 s42, s40, 3
	s_branch .Lpool_smp
.Lpool_snext:
	s_add_i32 s40, s40, s79
	s_branch .Lpool_sloop

; #define PG8_LAS __attribute__((address_space(3)))
;     __device__ __forceinline__ void operator()(const f32x4 (&acc)[2][2][4][2], const Unit& u, int wr, int wc, int fr, int fq) const {
;     ...
;         float rstd[2][4];
; #pragma unroll
;         for (int ai = 0; ai < 2; ++ai)
; #pragma unroll
;             for (int m = 0; m < 4; ++m) rstd[ai][m] = RSTD[u.idx * 256 + ai * HALF + wr * 64 + m * 16 + fr];
;         if (!smp) {
;             if (fr >= 14) {
; #pragma unroll
;                 for (int ai = 0; ai < 2; ++ai)
; #pragma unroll
;                     for (int n = 0; n < 2; ++n) *(PG8_LAS f32x4*)(xch + ((((ai * 2 + wr) * 4 + wc) * 4 + fq) * 2 + (fr - 14)) * 8 + 4 * n) = acc[ai][0][3][n] * rstd[ai][3]; }
;             asm volatile("s_waitcnt lgkmcnt(0)" ::: "memory"); __builtin_amdgcn_s_barrier(); asm volatile("" ::: "memory");
;         }
.LBB0_888:
	s_cmp_gt_i32 s28, 63
	s_cbranch_scc0 .Lepi5_hand
	v_lshl_add_u32 v86, s11, 10, v216
	ds_read2_b32 v[206:207], v86 offset1:16
	ds_read2_b32 v[200:201], v86 offset0:32 offset1:48
	ds_read2_b32 v[196:197], v86 offset0:128 offset1:144
	ds_read2_b32 v[192:193], v86 offset0:160 offset1:176
	s_cmp_gt_i32 s28, 63
	s_cselect_b64 s[74:75], -1, 0
	s_waitcnt lgkmcnt(0)
	v_mov_b32_e32 v204, v207
	v_mov_b32_e32 v198, v201
	v_mov_b32_e32 v194, v197
	v_mov_b32_e32 v188, v193
	s_mov_b64 s[70:71], 0
	s_and_b64 vcc, exec, s[74:75]
	s_cbranch_vccnz .LBB0_892
	s_and_saveexec_b64 s[2:3], s[26:27]
	s_cbranch_execz .LBB0_891
	v_pk_mul_f32 v[106:107], v[126:127], v[198:199] op_sel_hi:[1,0]
	v_pk_mul_f32 v[104:105], v[124:125], v[198:199] op_sel_hi:[1,0]
	v_add_u32_e32 v86, s51, v215
	ds_write_b128 v86, v[104:107]
	v_pk_mul_f32 v[106:107], v[40:41], v[198:199] op_sel_hi:[1,0]
	v_pk_mul_f32 v[104:105], v[38:39], v[198:199] op_sel_hi:[1,0]
	ds_write_b128 v86, v[104:107] offset:16
	v_pk_mul_f32 v[106:107], v[76:77], v[188:189] op_sel_hi:[1,0]
	v_pk_mul_f32 v[104:105], v[74:75], v[188:189] op_sel_hi:[1,0]
	ds_write_b128 v224, v[104:107]
	v_pk_mul_f32 v[106:107], v[8:9], v[188:189] op_sel_hi:[1,0]
	v_pk_mul_f32 v[104:105], v[6:7], v[188:189] op_sel_hi:[1,0]
	ds_write_b128 v224, v[104:107] offset:16

; #define PG8_LAS __attribute__((address_space(3)))
;     __device__ __forceinline__ void operator()(const f32x4 (&acc)[2][2][4][2], const Unit& u, int wr, int wc, int fr, int fq) const {
;     ...
;         float rstd[2][4];
; #pragma unroll
;         for (int ai = 0; ai < 2; ++ai)
; #pragma unroll
;             for (int m = 0; m < 4; ++m) rstd[ai][m] = RSTD[u.idx * 256 + ai * HALF + wr * 64 + m * 16 + fr];
;         if (!smp) {
;             if (fr >= 14) {
; #pragma unroll
;                 for (int ai = 0; ai < 2; ++ai)
; #pragma unroll
;                     for (int n = 0; n < 2; ++n) *(PG8_LAS f32x4*)(xch + ((((ai * 2 + wr) * 4 + wc) * 4 + fq) * 2 + (fr - 14)) * 8 + 4 * n) = acc[ai][0][3][n] * rstd[ai][3]; }
;             asm volatile("s_waitcnt lgkmcnt(0)" ::: "memory"); __builtin_amdgcn_s_barrier(); asm volatile("" ::: "memory");
;         }
;     ...
;         asm volatile("s_waitcnt vmcnt(0)" ::: "memory");
;         if (blockIdx.x == 0 && threadIdx.x == 0) ((volatile PG8_LAS unsigned long long*)((PG8_LAS unsigned char*)xch - 4096 + 512))[43] += __builtin_amdgcn_s_memrealtime() - pu_t0;
;     ...
;         auto ror1 = [](float v) -> float { return __builtin_bit_cast(float, __builtin_amdgcn_mov_dpp(__builtin_bit_cast(int, v), 0x121, 0xf, 0xf, true)); };
;         auto ror2 = [](float v) -> float { return __builtin_bit_cast(float, __builtin_amdgcn_mov_dpp(__builtin_bit_cast(int, v), 0x122, 0xf, 0xf, true)); };
;         u32x2 pk0[2][4];
; #pragma unroll
;         for (int n = 0; n < 2; ++n) {
;             const f32x4 cb = *(const f32x4*)(conv_b + j0 + 4 * n), w0 = *(const f32x4*)(conv_w + j0 + 4 * n), w1 = *(const f32x4*)(conv_w + FF + j0 + 4 * n), w2 = *(const f32x4*)(conv_w + 2 * FF + j0 + 4 * n);
.LBB0_1076:
	s_or_b64 exec, exec, s[28:29]
	v_mov_b32_e32 v14, v188
	v_mov_b32_e32 v15, v188
	v_pk_mul_f32 v[4:5], v[4:5], v[14:15]
	s_waitcnt vmcnt(0)
	v_pk_fma_f32 v[14:15], v[80:81], v[20:21], v[76:77]
	v_pk_fma_f32 v[16:17], v[78:79], v[18:19], v[74:75]
	v_pk_fma_f32 v[12:13], v[108:109], v[12:13], v[14:15]
	v_pk_fma_f32 v[10:11], v[106:107], v[10:11], v[16:17]
	v_pk_fma_f32 v[8:9], v[8:9], v[112:113], v[12:13]
	v_pk_fma_f32 v[6:7], v[6:7], v[110:111], v[10:11]
	v_pk_mul_f32 v[10:11], v[8:9], v[8:9]
	v_pk_mul_f32 v[12:13], v[6:7], v[6:7]
	v_mov_b64_e32 v[14:15], s[56:57]
	v_pk_fma_f32 v[10:11], v[10:11], s[58:59], v[14:15] op_sel_hi:[1,0,0]
	v_pk_fma_f32 v[12:13], v[12:13], s[58:59], v[14:15] op_sel_hi:[1,0,0]
	v_pk_mul_f32 v[10:11], v[8:9], v[10:11]
	v_pk_mul_f32 v[12:13], v[6:7], v[12:13]
	v_exp_f32_e32 v10, v10
	v_exp_f32_e32 v12, v12
	v_exp_f32_e32 v13, v13
	v_exp_f32_e32 v11, v11
	v_pk_mul_f32 v[2:3], v[2:3], v[188:189]
	v_add_f32_e32 v12, 1.0, v12
	v_add_f32_e32 v14, 1.0, v13
	v_add_f32_e32 v13, 1.0, v10
	v_add_f32_e32 v11, 1.0, v11
	v_rcp_f32_e32 v10, v12
	v_rcp_f32_e32 v12, v13
	v_rcp_f32_e32 v13, v11
	v_rcp_f32_e32 v11, v14
	v_add_u32_e32 v14, 0xb0, v226
	s_andn2_b64 vcc, exec, s[8:9]
	v_pk_mul_f32 v[8:9], v[8:9], v[12:13]
	v_pk_mul_f32 v[6:7], v[6:7], v[10:11]
	v_pk_mul_f32 v[4:5], v[4:5], v[8:9]
	v_pk_mul_f32 v[2:3], v[2:3], v[6:7]
	s_nop 0
	v_cvt_pk_bf16_f32 v68, v2, v3
	v_mov_b64_e32 v[2:3], s[14:15]
	v_mad_i64_i32 v[2:3], s[2:3], v14, s76, v[2:3]
	v_lshl_add_u64 v[2:3], v[190:191], 1, v[2:3]
	s_mov_b64 s[2:3], -1
	v_cvt_pk_bf16_f32 v69, v4, v5
	global_store_dwordx4 v[2:3], v[66:69], off
	s_branch .Lepi5_join
.Lepi5_hand:
	v_readfirstlane_b32 s70, v0
	v_readlane_b32 s82, v254, 50
	v_readlane_b32 s83, v254, 51
	v_readlane_b32 s84, v254, 52
	v_readlane_b32 s85, v254, 53
	v_readlane_b32 s86, v254, 19
	v_readlane_b32 s87, v254, 20
	v_and_b32_e32 v200, 15, v202
	v_lshrrev_b32_e32 v201, 4, v202
	s_nop 1
	v_cmp_lt_u32_e64 s[90:91], 13, v200
	v_cmp_gt_u32_e64 s[92:93], 2, v200
	v_cmp_eq_u32_e64 s[94:95], 0, v200
	s_lshr_b32 s70, s70, 6
	s_lshr_b32 s71, s70, 2
	s_and_b32 s72, s70, 3
	s_sub_u32 s86, s86, 0x4000
	s_subb_u32 s87, s87, 0
	s_lshl_b32 s73, s10, 7
	s_lshl_b32 s74, s72, 5
	s_add_i32 s73, s73, s74
	v_lshl_add_u32 v213, v201, 3, s73
	v_lshlrev_b32_e32 v213, 2, v213
	s_add_u32 s88, s82, 0x2c00
	s_addc_u32 s89, s83, 0
	s_add_u32 s34, s82, 0x5800
	s_addc_u32 s35, s83, 0
	global_load_dwordx4 v[226:229], v213, s[84:85]
	global_load_dwordx4 v[230:233], v213, s[84:85] offset:16
	global_load_dwordx4 v[234:237], v213, s[82:83]
	global_load_dwordx4 v[238:241], v213, s[82:83] offset:16
	global_load_dwordx4 v[242:245], v213, s[88:89]
	global_load_dwordx4 v[246:249], v213, s[88:89] offset:16
	global_load_dwordx4 v[250:253], v213, s[34:35]
	global_load_dwordx4 v[204:207], v213, s[34:35] offset:16
	s_lshl_b32 s73, s11, 10
	s_lshl_b32 s74, s71, 8
	s_add_i32 s73, s73, s74
	s_add_i32 s73, s73, 0x22000
	v_lshl_add_u32 v99, v200, 2, s73
	ds_read2_b32 v[152:153], v99 offset1:16
	ds_read2_b32 v[154:155], v99 offset0:32 offset1:48
	ds_read2_b32 v[156:157], v99 offset0:128 offset1:144
	ds_read2_b32 v[158:159], v99 offset0:160 offset1:176
	s_mul_i32 s74, s71, 0x58000
	v_lshrrev_b32_e32 v212, 1, v213
	v_add_u32_e32 v212, s74, v212
	s_movk_i32 s75, 0x1600
	v_mad_u32_u24 v212, v200, s75, v212
	s_waitcnt lgkmcnt(0)
	v_pk_mul_f32 v[148:149], v[148:149], v[152:153] op_sel_hi:[1,0]
	v_pk_mul_f32 v[150:151], v[150:151], v[152:153] op_sel_hi:[1,0]
	v_pk_mul_f32 v[62:63], v[62:63], v[152:153] op_sel_hi:[1,0]
	v_pk_mul_f32 v[64:65], v[64:65], v[152:153] op_sel_hi:[1,0]
	v_pk_mul_f32 v[144:145], v[144:145], v[152:153] op_sel_hi:[1,0]
	v_pk_mul_f32 v[146:147], v[146:147], v[152:153] op_sel_hi:[1,0]
	v_pk_mul_f32 v[58:59], v[58:59], v[152:153] op_sel_hi:[1,0]
	v_pk_mul_f32 v[60:61], v[60:61], v[152:153] op_sel_hi:[1,0]
	v_pk_mul_f32 v[140:141], v[140:141], v[152:153] op_sel:[0,1] op_sel_hi:[1,1]
	v_pk_mul_f32 v[142:143], v[142:143], v[152:153] op_sel:[0,1] op_sel_hi:[1,1]
	v_pk_mul_f32 v[54:55], v[54:55], v[152:153] op_sel:[0,1] op_sel_hi:[1,1]
	v_pk_mul_f32 v[56:57], v[56:57], v[152:153] op_sel:[0,1] op_sel_hi:[1,1]
	v_pk_mul_f32 v[136:137], v[136:137], v[152:153] op_sel:[0,1] op_sel_hi:[1,1]
	v_pk_mul_f32 v[138:139], v[138:139], v[152:153] op_sel:[0,1] op_sel_hi:[1,1]
	v_pk_mul_f32 v[50:51], v[50:51], v[152:153] op_sel:[0,1] op_sel_hi:[1,1]
	v_pk_mul_f32 v[52:53], v[52:53], v[152:153] op_sel:[0,1] op_sel_hi:[1,1]
	v_pk_mul_f32 v[132:133], v[132:133], v[154:155] op_sel_hi:[1,0]
	v_pk_mul_f32 v[134:135], v[134:135], v[154:155] op_sel_hi:[1,0]
	v_pk_mul_f32 v[46:47], v[46:47], v[154:155] op_sel_hi:[1,0]
	v_pk_mul_f32 v[48:49], v[48:49], v[154:155] op_sel_hi:[1,0]
	v_pk_mul_f32 v[128:129], v[128:129], v[154:155] op_sel_hi:[1,0]
	v_pk_mul_f32 v[130:131], v[130:131], v[154:155] op_sel_hi:[1,0]
	v_pk_mul_f32 v[42:43], v[42:43], v[154:155] op_sel_hi:[1,0]
	v_pk_mul_f32 v[44:45], v[44:45], v[154:155] op_sel_hi:[1,0]
	v_pk_mul_f32 v[124:125], v[124:125], v[154:155] op_sel:[0,1] op_sel_hi:[1,1]
	v_pk_mul_f32 v[126:127], v[126:127], v[154:155] op_sel:[0,1] op_sel_hi:[1,1]
	v_pk_mul_f32 v[38:39], v[38:39], v[154:155] op_sel:[0,1] op_sel_hi:[1,1]
	v_pk_mul_f32 v[40:41], v[40:41], v[154:155] op_sel:[0,1] op_sel_hi:[1,1]
	v_pk_mul_f32 v[94:95], v[94:95], v[154:155] op_sel:[0,1] op_sel_hi:[1,1]
	v_pk_mul_f32 v[96:97], v[96:97], v[154:155] op_sel:[0,1] op_sel_hi:[1,1]
	v_pk_mul_f32 v[34:35], v[34:35], v[154:155] op_sel:[0,1] op_sel_hi:[1,1]
	v_pk_mul_f32 v[36:37], v[36:37], v[154:155] op_sel:[0,1] op_sel_hi:[1,1]
	v_pk_mul_f32 v[120:121], v[120:121], v[156:157] op_sel_hi:[1,0]
; #define PG8_LAS __attribute__((address_space(3)))
;     __device__ __forceinline__ void operator()(const f32x4 (&acc)[2][2][4][2], const Unit& u, int wr, int wc, int fr, int fq) const {
;     ...
;             if (fr >= 14) {
; #pragma unroll
;                 for (int ai = 0; ai < 2; ++ai)
; #pragma unroll
;                     for (int n = 0; n < 2; ++n) *(PG8_LAS f32x4*)(xch + ((((ai * 2 + wr) * 4 + wc) * 4 + fq) * 2 + (fr - 14)) * 8 + 4 * n) = acc[ai][0][3][n] * rstd[ai][3]; }
;             asm volatile("s_waitcnt lgkmcnt(0)" ::: "memory"); __builtin_amdgcn_s_barrier(); asm volatile("" ::: "memory");
;         }
;     ...
;         asm volatile("s_waitcnt vmcnt(0)" ::: "memory");
;         if (blockIdx.x == 0 && threadIdx.x == 0) ((volatile PG8_LAS unsigned long long*)((PG8_LAS unsigned char*)xch - 4096 + 512))[43] += __builtin_amdgcn_s_memrealtime() - pu_t0;
;     ...
;         auto ror1 = [](float v) -> float { return __builtin_bit_cast(float, __builtin_amdgcn_mov_dpp(__builtin_bit_cast(int, v), 0x121, 0xf, 0xf, true)); };
;         auto ror2 = [](float v) -> float { return __builtin_bit_cast(float, __builtin_amdgcn_mov_dpp(__builtin_bit_cast(int, v), 0x122, 0xf, 0xf, true)); };
;         u32x2 pk0[2][4];
; #pragma unroll
;         for (int n = 0; n < 2; ++n) {
;             const f32x4 cb = *(const f32x4*)(conv_b + j0 + 4 * n), w0 = *(const f32x4*)(conv_w + j0 + 4 * n), w1 = *(const f32x4*)(conv_w + FF + j0 + 4 * n), w2 = *(const f32x4*)(conv_w + 2 * FF + j0 + 4 * n);
; #pragma unroll
;             for (int ai = 0; ai < 2; ++ai) {
;                 f32x4 pa = (f32x4){0.f, 0.f, 0.f, 0.f};
;                 if (!smp && fr >= 14 && (wr == 1 || ai == 1)) { const int sai = wr == 1 ? ai : 0, swr = wr == 1 ? 0 : 1;
;                     pa = *(const PG8_LAS f32x4*)(xch + ((((sai * 2 + swr) * 4 + wc) * 4 + fq) * 2 + (fr - 14)) * 8 + 4 * n); }
; #pragma unroll
;                 for (int m = 0; m < 4; ++m) {
;                     const int r = row0 + ai * HALF + m * 16; const float rs = rstd[ai][m];
;                     const f32x4 a = acc[ai][0][m][n] * rs, b = acc[ai][1][m][n] * rs; f32x4 p1, p2;
;                     if (!smp) {
; #pragma unroll
;                         for (int e2 = 0; e2 < 4; ++e2) { const float s1 = fr == 15 ? pa[e2] : a[e2], s2 = fr >= 14 ? pa[e2] : a[e2]; p1[e2] = ror1(s1); p2[e2] = ror2(s2); }
	v_pk_mul_f32 v[122:123], v[122:123], v[156:157] op_sel_hi:[1,0]
	v_pk_mul_f32 v[30:31], v[30:31], v[156:157] op_sel_hi:[1,0]
	v_pk_mul_f32 v[32:33], v[32:33], v[156:157] op_sel_hi:[1,0]
	v_pk_mul_f32 v[100:101], v[100:101], v[156:157] op_sel_hi:[1,0]
	v_pk_mul_f32 v[102:103], v[102:103], v[156:157] op_sel_hi:[1,0]
	v_pk_mul_f32 v[26:27], v[26:27], v[156:157] op_sel_hi:[1,0]
	v_pk_mul_f32 v[28:29], v[28:29], v[156:157] op_sel_hi:[1,0]
	v_pk_mul_f32 v[88:89], v[88:89], v[156:157] op_sel:[0,1] op_sel_hi:[1,1]
	v_pk_mul_f32 v[90:91], v[90:91], v[156:157] op_sel:[0,1] op_sel_hi:[1,1]
	v_pk_mul_f32 v[22:23], v[22:23], v[156:157] op_sel:[0,1] op_sel_hi:[1,1]
	v_pk_mul_f32 v[24:25], v[24:25], v[156:157] op_sel:[0,1] op_sel_hi:[1,1]
	v_pk_mul_f32 v[82:83], v[82:83], v[156:157] op_sel:[0,1] op_sel_hi:[1,1]
	v_pk_mul_f32 v[84:85], v[84:85], v[156:157] op_sel:[0,1] op_sel_hi:[1,1]
	v_pk_mul_f32 v[18:19], v[18:19], v[156:157] op_sel:[0,1] op_sel_hi:[1,1]
	v_pk_mul_f32 v[20:21], v[20:21], v[156:157] op_sel:[0,1] op_sel_hi:[1,1]
	v_pk_mul_f32 v[78:79], v[78:79], v[158:159] op_sel_hi:[1,0]
	v_pk_mul_f32 v[80:81], v[80:81], v[158:159] op_sel_hi:[1,0]
	v_pk_mul_f32 v[14:15], v[14:15], v[158:159] op_sel_hi:[1,0]
	v_pk_mul_f32 v[16:17], v[16:17], v[158:159] op_sel_hi:[1,0]
	v_pk_mul_f32 v[70:71], v[70:71], v[158:159] op_sel_hi:[1,0]
	v_pk_mul_f32 v[72:73], v[72:73], v[158:159] op_sel_hi:[1,0]
	v_pk_mul_f32 v[10:11], v[10:11], v[158:159] op_sel_hi:[1,0]
	v_pk_mul_f32 v[12:13], v[12:13], v[158:159] op_sel_hi:[1,0]
	v_pk_mul_f32 v[74:75], v[74:75], v[158:159] op_sel:[0,1] op_sel_hi:[1,1]
	v_pk_mul_f32 v[76:77], v[76:77], v[158:159] op_sel:[0,1] op_sel_hi:[1,1]
	v_pk_mul_f32 v[6:7], v[6:7], v[158:159] op_sel:[0,1] op_sel_hi:[1,1]
	v_pk_mul_f32 v[8:9], v[8:9], v[158:159] op_sel:[0,1] op_sel_hi:[1,1]
	v_pk_mul_f32 v[66:67], v[66:67], v[158:159] op_sel:[0,1] op_sel_hi:[1,1]
	v_pk_mul_f32 v[68:69], v[68:69], v[158:159] op_sel:[0,1] op_sel_hi:[1,1]
	v_pk_mul_f32 v[2:3], v[2:3], v[158:159] op_sel:[0,1] op_sel_hi:[1,1]
	v_pk_mul_f32 v[4:5], v[4:5], v[158:159] op_sel:[0,1] op_sel_hi:[1,1]
	s_lshl_b32 s73, s70, 8
	s_add_i32 s73, s73, 0x20e40
	v_lshlrev_b32_e32 v99, 6, v201
	v_lshl_add_u32 v99, v200, 5, v99
	v_mov_b32_e32 v188, 0
	v_mov_b32_e32 v189, 0
	v_mov_b32_e32 v190, 0
	v_mov_b32_e32 v191, 0
	v_mov_b32_e32 v192, 0
	v_mov_b32_e32 v193, 0
	v_mov_b32_e32 v194, 0
	v_mov_b32_e32 v195, 0
	v_mov_b32_e32 v196, 0
	v_mov_b32_e32 v197, 0
	v_mov_b32_e32 v198, 0
	v_mov_b32_e32 v199, 0
	v_mov_b32_e32 v160, 0
	v_mov_b32_e32 v161, 0
	v_mov_b32_e32 v162, 0
	v_mov_b32_e32 v163, 0
	v_add_u32_e32 v86, s73, v99
	s_mov_b64 exec, s[90:91]
	ds_write_b128 v86, v[124:127]
	ds_write_b128 v86, v[38:41] offset:16
	ds_write_b128 v86, v[74:77] offset:2048
	ds_write_b128 v86, v[6:9] offset:2064
	s_mov_b64 exec, -1
	s_waitcnt lgkmcnt(0)
	s_barrier
	s_lshl_b32 s73, s72, 8
	s_add_i32 s73, s73, 0x20e40
	v_add_u32_e32 v86, s73, v99
	s_mov_b64 exec, s[90:91]
	s_cmp_eq_u32 s71, 0
	s_cbranch_scc1 .Lepi5_pa_wr0
	ds_read_b128 v[188:191], v86
	ds_read_b128 v[192:195], v86 offset:16
	ds_read_b128 v[196:199], v86 offset:2048
	ds_read_b128 v[160:163], v86 offset:2064
	s_branch .Lepi5_pa_done
.Lepi5_pa_wr0:
	ds_read_b128 v[196:199], v86 offset:1024
	ds_read_b128 v[160:163], v86 offset:1040
.Lepi5_pa_done:
	s_mov_b64 exec, -1
	s_waitcnt vmcnt(0)
	v_cndmask_b32_e64 v104, 0, v242, s[94:95]
	v_cndmask_b32_e64 v112, 0, v234, s[92:93]
	v_cndmask_b32_e64 v105, 0, v243, s[94:95]
	v_cndmask_b32_e64 v113, 0, v235, s[92:93]
	v_cndmask_b32_e64 v106, 0, v244, s[94:95]
	v_cndmask_b32_e64 v114, 0, v236, s[92:93]
	v_cndmask_b32_e64 v107, 0, v245, s[94:95]
	v_cndmask_b32_e64 v115, 0, v237, s[92:93]
	v_cndmask_b32_e64 v108, 0, v246, s[94:95]
	v_cndmask_b32_e64 v116, 0, v238, s[92:93]
	v_cndmask_b32_e64 v109, 0, v247, s[94:95]
	v_cndmask_b32_e64 v117, 0, v239, s[92:93]
	v_cndmask_b32_e64 v110, 0, v248, s[94:95]
	v_cndmask_b32_e64 v118, 0, v240, s[92:93]
	v_cndmask_b32_e64 v111, 0, v249, s[94:95]
	v_cndmask_b32_e64 v119, 0, v241, s[92:93]
	v_mov_b32_e32 v98, 0xc0135761
	s_mul_i32 s73, s28, 0x160000
	s_add_u32 s80, s86, 0x9e00000
	s_addc_u32 s81, s87, 0
	s_add_u32 s80, s80, s73
	s_addc_u32 s81, s81, 0
	s_waitcnt lgkmcnt(0)
	s_cmp_lg_u32 s71, 0
	s_cbranch_scc1 .Lepi5_noedge0
	s_movk_i32 s75, 0x2c00
	v_mad_u32_u24 v99, v200, s75, v213
	s_mul_i32 s73, s28, 0xb000
	s_add_u32 s88, s86, 0x4000000
	s_addc_u32 s89, s87, 0
	s_add_u32 s88, s88, s73
	s_addc_u32 s89, s89, 0
	s_mul_i32 s73, s28, 0x5800
	s_add_u32 s34, s86, 0x4400000
	s_addc_u32 s35, s87, 0
	s_add_u32 s34, s34, s73
	s_addc_u32 s35, s35, 0
	s_mov_b64 exec, s[92:93]
	global_store_dwordx4 v99, v[148:151], s[88:89]
	global_store_dwordx4 v99, v[62:65], s[88:89] offset:16
	global_store_dwordx4 v99, v[144:147], s[34:35]
	global_store_dwordx4 v99, v[58:61], s[34:35] offset:16
	s_mov_b64 exec, -1
;     __device__ __forceinline__ void operator()(const f32x4 (&acc)[2][2][4][2], const Unit& u, int wr, int wc, int fr, int fq) const {
;     ...
;                 for (int m = 0; m < 4; ++m) {
;                     const int r = row0 + ai * HALF + m * 16; const float rs = rstd[ai][m];
;                     const f32x4 a = acc[ai][0][m][n] * rs, b = acc[ai][1][m][n] * rs; f32x4 p1, p2;
;                     if (!smp) {
; #pragma unroll
;                         for (int e2 = 0; e2 < 4; ++e2) { const float s1 = fr == 15 ? pa[e2] : a[e2], s2 = fr >= 14 ? pa[e2] : a[e2]; p1[e2] = ror1(s1); p2[e2] = ror2(s2); }
;                         if (ai == 0 && wr == 0 && m == 0 && fr < 2) { *(f32x4*)(EA + ((size_t)u.pm * 4 + fr) * FF + j0 + 4 * n) = a; *(f32x4*)(EB + ((size_t)u.pm * 2 + fr) * FF + j0 + 4 * n) = b; }
;                         if (ai == 1 && wr == 1 && m == 3 && fr >= 14) { *(f32x4*)(EA + ((size_t)u.pm * 4 + 2 + (fr - 14)) * FF + j0 + 4 * n) = a;
;                             if ((u.pm & 7) == 7) *(f32x4*)(o_conv_p + ((size_t)(u.pm >> 3) * 2 + (fr - 14)) * FF + j0 + 4 * n) = a; }
;                     } else {
;                         const int t = fr & 7, bb = (r - 16384) >> 3;
; #pragma unroll
;                         for (int e2 = 0; e2 < 4; ++e2) { p1[e2] = ror1(a[e2]); p2[e2] = ror2(a[e2]); }
;                         if (t < 2) { const f32x4 h1 = *(const f32x4*)(state_conv + ((size_t)bb * 2 + 1) * FF + j0 + 4 * n);
;                             if (t == 0) { p1 = h1; p2 = *(const f32x4*)(state_conv + ((size_t)bb * 2) * FF + j0 + 4 * n); } else p2 = h1; }
;                         if (t >= 6) *(f32x4*)(o_conv_s + ((size_t)bb * 2 + (t - 6)) * FF + j0 + 4 * n) = a;
;                     }
;                     f32x4 hv;
; #pragma unroll
;                     for (int e2 = 0; e2 < 1; ++e2) {
;                         const f32x4 c4 = cb + w0 * p2 + w1 * p1 + w2 * a;
;                         const f32x4 z = c4 * ((c4 * c4) * (-0.10294324f) + (-2.3022082f));
;                         f32x4 den; den[0] = 1.f + __builtin_amdgcn_exp2f(z[0]); den[1] = 1.f + __builtin_amdgcn_exp2f(z[1]); den[2] = 1.f + __builtin_amdgcn_exp2f(z[2]); den[3] = 1.f + __builtin_amdgcn_exp2f(z[3]);
;                         f32x4 rc; rc[0] = frcp(den[0]); rc[1] = frcp(den[1]); rc[2] = frcp(den[2]); rc[3] = frcp(den[3]);
;                         hv = (c4 * rc) * b; }
.Lepi5_noedge0:
	v_fma_f32 v208, v148, v250, v226
	v_fma_f32 v209, v149, v251, v227
	v_fma_f32 v210, v150, v252, v228
	v_fma_f32 v211, v151, v253, v229
	v_fmac_f32_dpp v208, v148, v242 row_shr:1 row_mask:0xf bank_mask:0xf
	v_fmac_f32_dpp v209, v149, v243 row_shr:1 row_mask:0xf bank_mask:0xf
	v_fmac_f32_dpp v210, v150, v244 row_shr:1 row_mask:0xf bank_mask:0xf
	v_fmac_f32_dpp v211, v151, v245 row_shr:1 row_mask:0xf bank_mask:0xf
	v_fmac_f32_dpp v208, v148, v234 row_shr:2 row_mask:0xf bank_mask:0xf
	v_fmac_f32_dpp v209, v149, v235 row_shr:2 row_mask:0xf bank_mask:0xf
	v_fmac_f32_dpp v210, v150, v236 row_shr:2 row_mask:0xf bank_mask:0xf
	v_fmac_f32_dpp v211, v151, v237 row_shr:2 row_mask:0xf bank_mask:0xf
	v_fmac_f32_dpp v208, v188, v104 row_ror:1 row_mask:0xf bank_mask:0xf
	v_fmac_f32_dpp v209, v189, v105 row_ror:1 row_mask:0xf bank_mask:0xf
	v_fmac_f32_dpp v210, v190, v106 row_ror:1 row_mask:0xf bank_mask:0xf
	v_fmac_f32_dpp v211, v191, v107 row_ror:1 row_mask:0xf bank_mask:0xf
	v_fmac_f32_dpp v208, v188, v112 row_ror:2 row_mask:0xf bank_mask:0xf
	v_fmac_f32_dpp v209, v189, v113 row_ror:2 row_mask:0xf bank_mask:0xf
	v_fmac_f32_dpp v210, v190, v114 row_ror:2 row_mask:0xf bank_mask:0xf
	v_fmac_f32_dpp v211, v191, v115 row_ror:2 row_mask:0xf bank_mask:0xf
	v_mul_f32_e32 v86, v208, v208
	v_mul_f32_e32 v87, v209, v209
	v_mul_f32_e32 v92, v210, v210
	v_mul_f32_e32 v93, v211, v211
	v_fmamk_f32 v86, v86, 0xbdd2d3e8, v98
	v_fmamk_f32 v87, v87, 0xbdd2d3e8, v98
	v_fmamk_f32 v92, v92, 0xbdd2d3e8, v98
	v_fmamk_f32 v93, v93, 0xbdd2d3e8, v98
	v_mul_f32_e32 v86, v208, v86
	v_mul_f32_e32 v87, v209, v87
	v_mul_f32_e32 v92, v210, v92
	v_mul_f32_e32 v93, v211, v93
	v_exp_f32_e32 v86, v86
	v_exp_f32_e32 v87, v87
	v_exp_f32_e32 v92, v92
	v_exp_f32_e32 v93, v93
	v_mul_f32_e32 v208, v208, v144
	v_mul_f32_e32 v209, v209, v145
	v_mul_f32_e32 v210, v210, v146
	v_mul_f32_e32 v211, v211, v147
	v_add_f32_e32 v86, 1.0, v86
	v_add_f32_e32 v87, 1.0, v87
	v_add_f32_e32 v92, 1.0, v92
	v_add_f32_e32 v93, 1.0, v93
	v_rcp_f32_e32 v86, v86
	v_rcp_f32_e32 v87, v87
	v_rcp_f32_e32 v92, v92
	v_rcp_f32_e32 v93, v93
	s_nop 0
	v_mul_f32_e32 v208, v208, v86
	v_mul_f32_e32 v209, v209, v87
	v_mul_f32_e32 v210, v210, v92
	v_mul_f32_e32 v211, v211, v93
	v_cvt_pk_bf16_f32 v144, v208, v209
	v_cvt_pk_bf16_f32 v145, v210, v211
	v_fma_f32 v208, v62, v204, v230
	v_fma_f32 v209, v63, v205, v231
	v_fma_f32 v210, v64, v206, v232
	v_fma_f32 v211, v65, v207, v233
	v_fmac_f32_dpp v208, v62, v246 row_shr:1 row_mask:0xf bank_mask:0xf
	v_fmac_f32_dpp v209, v63, v247 row_shr:1 row_mask:0xf bank_mask:0xf
	v_fmac_f32_dpp v210, v64, v248 row_shr:1 row_mask:0xf bank_mask:0xf
	v_fmac_f32_dpp v211, v65, v249 row_shr:1 row_mask:0xf bank_mask:0xf
	v_fmac_f32_dpp v208, v62, v238 row_shr:2 row_mask:0xf bank_mask:0xf
	v_fmac_f32_dpp v209, v63, v239 row_shr:2 row_mask:0xf bank_mask:0xf
	v_fmac_f32_dpp v210, v64, v240 row_shr:2 row_mask:0xf bank_mask:0xf
	v_fmac_f32_dpp v211, v65, v241 row_shr:2 row_mask:0xf bank_mask:0xf
	v_fmac_f32_dpp v208, v192, v108 row_ror:1 row_mask:0xf bank_mask:0xf
	v_fmac_f32_dpp v209, v193, v109 row_ror:1 row_mask:0xf bank_mask:0xf
	v_fmac_f32_dpp v210, v194, v110 row_ror:1 row_mask:0xf bank_mask:0xf
	v_fmac_f32_dpp v211, v195, v111 row_ror:1 row_mask:0xf bank_mask:0xf
	v_fmac_f32_dpp v208, v192, v116 row_ror:2 row_mask:0xf bank_mask:0xf
	v_fmac_f32_dpp v209, v193, v117 row_ror:2 row_mask:0xf bank_mask:0xf
	v_fmac_f32_dpp v210, v194, v118 row_ror:2 row_mask:0xf bank_mask:0xf
	v_fmac_f32_dpp v211, v195, v119 row_ror:2 row_mask:0xf bank_mask:0xf
	v_mul_f32_e32 v86, v208, v208
	v_mul_f32_e32 v87, v209, v209
	v_mul_f32_e32 v92, v210, v210
	v_mul_f32_e32 v93, v211, v211
	v_fmamk_f32 v86, v86, 0xbdd2d3e8, v98
	v_fmamk_f32 v87, v87, 0xbdd2d3e8, v98
	v_fmamk_f32 v92, v92, 0xbdd2d3e8, v98
	v_fmamk_f32 v93, v93, 0xbdd2d3e8, v98
	v_mul_f32_e32 v86, v208, v86
	v_mul_f32_e32 v87, v209, v87
	v_mul_f32_e32 v92, v210, v92
	v_mul_f32_e32 v93, v211, v93
	v_exp_f32_e32 v86, v86
	v_exp_f32_e32 v87, v87
	v_exp_f32_e32 v92, v92
	v_exp_f32_e32 v93, v93
	v_mul_f32_e32 v208, v208, v58
	v_mul_f32_e32 v209, v209, v59
	v_mul_f32_e32 v210, v210, v60
	v_mul_f32_e32 v211, v211, v61
	v_add_f32_e32 v86, 1.0, v86
	v_add_f32_e32 v87, 1.0, v87
	v_add_f32_e32 v92, 1.0, v92
	v_add_f32_e32 v93, 1.0, v93
	v_rcp_f32_e32 v86, v86
	v_rcp_f32_e32 v87, v87
	v_rcp_f32_e32 v92, v92
	v_rcp_f32_e32 v93, v93
	s_nop 0
	v_mul_f32_e32 v208, v208, v86
	v_mul_f32_e32 v209, v209, v87
	v_mul_f32_e32 v210, v210, v92
	v_mul_f32_e32 v211, v211, v93
	v_cvt_pk_bf16_f32 v146, v208, v209
	v_cvt_pk_bf16_f32 v147, v210, v211
	global_store_dwordx4 v212, v[144:147], s[80:81]
	s_add_u32 s80, s80, 0x16000
	s_addc_u32 s81, s81, 0
	v_fma_f32 v208, v140, v250, v226
	v_fma_f32 v209, v141, v251, v227
	v_fma_f32 v210, v142, v252, v228
	v_fma_f32 v211, v143, v253, v229
	v_fmac_f32_dpp v208, v140, v242 row_shr:1 row_mask:0xf bank_mask:0xf
	v_fmac_f32_dpp v209, v141, v243 row_shr:1 row_mask:0xf bank_mask:0xf
	v_fmac_f32_dpp v210, v142, v244 row_shr:1 row_mask:0xf bank_mask:0xf
	v_fmac_f32_dpp v211, v143, v245 row_shr:1 row_mask:0xf bank_mask:0xf
	v_fmac_f32_dpp v208, v140, v234 row_shr:2 row_mask:0xf bank_mask:0xf
	v_fmac_f32_dpp v209, v141, v235 row_shr:2 row_mask:0xf bank_mask:0xf
	v_fmac_f32_dpp v210, v142, v236 row_shr:2 row_mask:0xf bank_mask:0xf
	v_fmac_f32_dpp v211, v143, v237 row_shr:2 row_mask:0xf bank_mask:0xf
	v_fmac_f32_dpp v208, v148, v104 row_ror:1 row_mask:0xf bank_mask:0xf
	v_fmac_f32_dpp v209, v149, v105 row_ror:1 row_mask:0xf bank_mask:0xf
	v_fmac_f32_dpp v210, v150, v106 row_ror:1 row_mask:0xf bank_mask:0xf
	v_fmac_f32_dpp v211, v151, v107 row_ror:1 row_mask:0xf bank_mask:0xf
;     __device__ __forceinline__ void operator()(const f32x4 (&acc)[2][2][4][2], const Unit& u, int wr, int wc, int fr, int fq) const {
;     ...
;                 for (int m = 0; m < 4; ++m) {
;                     const int r = row0 + ai * HALF + m * 16; const float rs = rstd[ai][m];
;                     const f32x4 a = acc[ai][0][m][n] * rs, b = acc[ai][1][m][n] * rs; f32x4 p1, p2;
;                     if (!smp) {
; #pragma unroll
;                         for (int e2 = 0; e2 < 4; ++e2) { const float s1 = fr == 15 ? pa[e2] : a[e2], s2 = fr >= 14 ? pa[e2] : a[e2]; p1[e2] = ror1(s1); p2[e2] = ror2(s2); }
;                         if (ai == 0 && wr == 0 && m == 0 && fr < 2) { *(f32x4*)(EA + ((size_t)u.pm * 4 + fr) * FF + j0 + 4 * n) = a; *(f32x4*)(EB + ((size_t)u.pm * 2 + fr) * FF + j0 + 4 * n) = b; }
;                         if (ai == 1 && wr == 1 && m == 3 && fr >= 14) { *(f32x4*)(EA + ((size_t)u.pm * 4 + 2 + (fr - 14)) * FF + j0 + 4 * n) = a;
;                             if ((u.pm & 7) == 7) *(f32x4*)(o_conv_p + ((size_t)(u.pm >> 3) * 2 + (fr - 14)) * FF + j0 + 4 * n) = a; }
;                     } else {
;                         const int t = fr & 7, bb = (r - 16384) >> 3;
; #pragma unroll
;                         for (int e2 = 0; e2 < 4; ++e2) { p1[e2] = ror1(a[e2]); p2[e2] = ror2(a[e2]); }
;                         if (t < 2) { const f32x4 h1 = *(const f32x4*)(state_conv + ((size_t)bb * 2 + 1) * FF + j0 + 4 * n);
;                             if (t == 0) { p1 = h1; p2 = *(const f32x4*)(state_conv + ((size_t)bb * 2) * FF + j0 + 4 * n); } else p2 = h1; }
;                         if (t >= 6) *(f32x4*)(o_conv_s + ((size_t)bb * 2 + (t - 6)) * FF + j0 + 4 * n) = a;
;                     }
;                     f32x4 hv;
; #pragma unroll
;                     for (int e2 = 0; e2 < 1; ++e2) {
;                         const f32x4 c4 = cb + w0 * p2 + w1 * p1 + w2 * a;
;                         const f32x4 z = c4 * ((c4 * c4) * (-0.10294324f) + (-2.3022082f));
;                         f32x4 den; den[0] = 1.f + __builtin_amdgcn_exp2f(z[0]); den[1] = 1.f + __builtin_amdgcn_exp2f(z[1]); den[2] = 1.f + __builtin_amdgcn_exp2f(z[2]); den[3] = 1.f + __builtin_amdgcn_exp2f(z[3]);
;                         f32x4 rc; rc[0] = frcp(den[0]); rc[1] = frcp(den[1]); rc[2] = frcp(den[2]); rc[3] = frcp(den[3]);
;                         hv = (c4 * rc) * b; }
	v_fmac_f32_dpp v208, v148, v112 row_ror:2 row_mask:0xf bank_mask:0xf
	v_fmac_f32_dpp v209, v149, v113 row_ror:2 row_mask:0xf bank_mask:0xf
	v_fmac_f32_dpp v210, v150, v114 row_ror:2 row_mask:0xf bank_mask:0xf
	v_fmac_f32_dpp v211, v151, v115 row_ror:2 row_mask:0xf bank_mask:0xf
	v_mul_f32_e32 v86, v208, v208
	v_mul_f32_e32 v87, v209, v209
	v_mul_f32_e32 v92, v210, v210
	v_mul_f32_e32 v93, v211, v211
	v_fmamk_f32 v86, v86, 0xbdd2d3e8, v98
	v_fmamk_f32 v87, v87, 0xbdd2d3e8, v98
	v_fmamk_f32 v92, v92, 0xbdd2d3e8, v98
	v_fmamk_f32 v93, v93, 0xbdd2d3e8, v98
	v_mul_f32_e32 v86, v208, v86
	v_mul_f32_e32 v87, v209, v87
	v_mul_f32_e32 v92, v210, v92
	v_mul_f32_e32 v93, v211, v93
	v_exp_f32_e32 v86, v86
	v_exp_f32_e32 v87, v87
	v_exp_f32_e32 v92, v92
	v_exp_f32_e32 v93, v93
	v_mul_f32_e32 v208, v208, v136
	v_mul_f32_e32 v209, v209, v137
	v_mul_f32_e32 v210, v210, v138
	v_mul_f32_e32 v211, v211, v139
	v_add_f32_e32 v86, 1.0, v86
	v_add_f32_e32 v87, 1.0, v87
	v_add_f32_e32 v92, 1.0, v92
	v_add_f32_e32 v93, 1.0, v93
	v_rcp_f32_e32 v86, v86
	v_rcp_f32_e32 v87, v87
	v_rcp_f32_e32 v92, v92
	v_rcp_f32_e32 v93, v93
	s_nop 0
	v_mul_f32_e32 v208, v208, v86
	v_mul_f32_e32 v209, v209, v87
	v_mul_f32_e32 v210, v210, v92
	v_mul_f32_e32 v211, v211, v93
	v_cvt_pk_bf16_f32 v136, v208, v209
	v_cvt_pk_bf16_f32 v137, v210, v211
	v_fma_f32 v208, v54, v204, v230
	v_fma_f32 v209, v55, v205, v231
	v_fma_f32 v210, v56, v206, v232
	v_fma_f32 v211, v57, v207, v233
	v_fmac_f32_dpp v208, v54, v246 row_shr:1 row_mask:0xf bank_mask:0xf
	v_fmac_f32_dpp v209, v55, v247 row_shr:1 row_mask:0xf bank_mask:0xf
	v_fmac_f32_dpp v210, v56, v248 row_shr:1 row_mask:0xf bank_mask:0xf
	v_fmac_f32_dpp v211, v57, v249 row_shr:1 row_mask:0xf bank_mask:0xf
	v_fmac_f32_dpp v208, v54, v238 row_shr:2 row_mask:0xf bank_mask:0xf
	v_fmac_f32_dpp v209, v55, v239 row_shr:2 row_mask:0xf bank_mask:0xf
	v_fmac_f32_dpp v210, v56, v240 row_shr:2 row_mask:0xf bank_mask:0xf
	v_fmac_f32_dpp v211, v57, v241 row_shr:2 row_mask:0xf bank_mask:0xf
	v_fmac_f32_dpp v208, v62, v108 row_ror:1 row_mask:0xf bank_mask:0xf
	v_fmac_f32_dpp v209, v63, v109 row_ror:1 row_mask:0xf bank_mask:0xf
	v_fmac_f32_dpp v210, v64, v110 row_ror:1 row_mask:0xf bank_mask:0xf
	v_fmac_f32_dpp v211, v65, v111 row_ror:1 row_mask:0xf bank_mask:0xf
	v_fmac_f32_dpp v208, v62, v116 row_ror:2 row_mask:0xf bank_mask:0xf
	v_fmac_f32_dpp v209, v63, v117 row_ror:2 row_mask:0xf bank_mask:0xf
	v_fmac_f32_dpp v210, v64, v118 row_ror:2 row_mask:0xf bank_mask:0xf
	v_fmac_f32_dpp v211, v65, v119 row_ror:2 row_mask:0xf bank_mask:0xf
	v_mul_f32_e32 v86, v208, v208
	v_mul_f32_e32 v87, v209, v209
	v_mul_f32_e32 v92, v210, v210
	v_mul_f32_e32 v93, v211, v211
	v_fmamk_f32 v86, v86, 0xbdd2d3e8, v98
	v_fmamk_f32 v87, v87, 0xbdd2d3e8, v98
	v_fmamk_f32 v92, v92, 0xbdd2d3e8, v98
	v_fmamk_f32 v93, v93, 0xbdd2d3e8, v98
	v_mul_f32_e32 v86, v208, v86
	v_mul_f32_e32 v87, v209, v87
	v_mul_f32_e32 v92, v210, v92
	v_mul_f32_e32 v93, v211, v93
	v_exp_f32_e32 v86, v86
	v_exp_f32_e32 v87, v87
	v_exp_f32_e32 v92, v92
	v_exp_f32_e32 v93, v93
	v_mul_f32_e32 v208, v208, v50
	v_mul_f32_e32 v209, v209, v51
	v_mul_f32_e32 v210, v210, v52
	v_mul_f32_e32 v211, v211, v53
	v_add_f32_e32 v86, 1.0, v86
	v_add_f32_e32 v87, 1.0, v87
	v_add_f32_e32 v92, 1.0, v92
	v_add_f32_e32 v93, 1.0, v93
	v_rcp_f32_e32 v86, v86
	v_rcp_f32_e32 v87, v87
	v_rcp_f32_e32 v92, v92
	v_rcp_f32_e32 v93, v93
	s_nop 0
	v_mul_f32_e32 v208, v208, v86
	v_mul_f32_e32 v209, v209, v87
	v_mul_f32_e32 v210, v210, v92
	v_mul_f32_e32 v211, v211, v93
	v_cvt_pk_bf16_f32 v138, v208, v209
	v_cvt_pk_bf16_f32 v139, v210, v211
	global_store_dwordx4 v212, v[136:139], s[80:81]
	s_add_u32 s80, s80, 0x16000
	s_addc_u32 s81, s81, 0
	v_fma_f32 v208, v132, v250, v226
	v_fma_f32 v209, v133, v251, v227
	v_fma_f32 v210, v134, v252, v228
	v_fma_f32 v211, v135, v253, v229
	v_fmac_f32_dpp v208, v132, v242 row_shr:1 row_mask:0xf bank_mask:0xf
	v_fmac_f32_dpp v209, v133, v243 row_shr:1 row_mask:0xf bank_mask:0xf
	v_fmac_f32_dpp v210, v134, v244 row_shr:1 row_mask:0xf bank_mask:0xf
	v_fmac_f32_dpp v211, v135, v245 row_shr:1 row_mask:0xf bank_mask:0xf
	v_fmac_f32_dpp v208, v132, v234 row_shr:2 row_mask:0xf bank_mask:0xf
	v_fmac_f32_dpp v209, v133, v235 row_shr:2 row_mask:0xf bank_mask:0xf
	v_fmac_f32_dpp v210, v134, v236 row_shr:2 row_mask:0xf bank_mask:0xf
	v_fmac_f32_dpp v211, v135, v237 row_shr:2 row_mask:0xf bank_mask:0xf
	v_fmac_f32_dpp v208, v140, v104 row_ror:1 row_mask:0xf bank_mask:0xf
	v_fmac_f32_dpp v209, v141, v105 row_ror:1 row_mask:0xf bank_mask:0xf
	v_fmac_f32_dpp v210, v142, v106 row_ror:1 row_mask:0xf bank_mask:0xf
	v_fmac_f32_dpp v211, v143, v107 row_ror:1 row_mask:0xf bank_mask:0xf
	v_fmac_f32_dpp v208, v140, v112 row_ror:2 row_mask:0xf bank_mask:0xf
	v_fmac_f32_dpp v209, v141, v113 row_ror:2 row_mask:0xf bank_mask:0xf
	v_fmac_f32_dpp v210, v142, v114 row_ror:2 row_mask:0xf bank_mask:0xf
	v_fmac_f32_dpp v211, v143, v115 row_ror:2 row_mask:0xf bank_mask:0xf
	v_mul_f32_e32 v86, v208, v208
	v_mul_f32_e32 v87, v209, v209
	v_mul_f32_e32 v92, v210, v210
	v_mul_f32_e32 v93, v211, v211
	v_fmamk_f32 v86, v86, 0xbdd2d3e8, v98
	v_fmamk_f32 v87, v87, 0xbdd2d3e8, v98
	v_fmamk_f32 v92, v92, 0xbdd2d3e8, v98
	v_fmamk_f32 v93, v93, 0xbdd2d3e8, v98
	v_mul_f32_e32 v86, v208, v86
	v_mul_f32_e32 v87, v209, v87
	v_mul_f32_e32 v92, v210, v92
	v_mul_f32_e32 v93, v211, v93
	v_exp_f32_e32 v86, v86
	v_exp_f32_e32 v87, v87
	v_exp_f32_e32 v92, v92
	v_exp_f32_e32 v93, v93
	v_mul_f32_e32 v208, v208, v128
	v_mul_f32_e32 v209, v209, v129
	v_mul_f32_e32 v210, v210, v130
	v_mul_f32_e32 v211, v211, v131
	v_add_f32_e32 v86, 1.0, v86
	v_add_f32_e32 v87, 1.0, v87
;     __device__ __forceinline__ void operator()(const f32x4 (&acc)[2][2][4][2], const Unit& u, int wr, int wc, int fr, int fq) const {
;     ...
;                 for (int m = 0; m < 4; ++m) {
;                     const int r = row0 + ai * HALF + m * 16; const float rs = rstd[ai][m];
;                     const f32x4 a = acc[ai][0][m][n] * rs, b = acc[ai][1][m][n] * rs; f32x4 p1, p2;
;                     if (!smp) {
; #pragma unroll
;                         for (int e2 = 0; e2 < 4; ++e2) { const float s1 = fr == 15 ? pa[e2] : a[e2], s2 = fr >= 14 ? pa[e2] : a[e2]; p1[e2] = ror1(s1); p2[e2] = ror2(s2); }
;                         if (ai == 0 && wr == 0 && m == 0 && fr < 2) { *(f32x4*)(EA + ((size_t)u.pm * 4 + fr) * FF + j0 + 4 * n) = a; *(f32x4*)(EB + ((size_t)u.pm * 2 + fr) * FF + j0 + 4 * n) = b; }
;                         if (ai == 1 && wr == 1 && m == 3 && fr >= 14) { *(f32x4*)(EA + ((size_t)u.pm * 4 + 2 + (fr - 14)) * FF + j0 + 4 * n) = a;
;                             if ((u.pm & 7) == 7) *(f32x4*)(o_conv_p + ((size_t)(u.pm >> 3) * 2 + (fr - 14)) * FF + j0 + 4 * n) = a; }
;                     } else {
;                         const int t = fr & 7, bb = (r - 16384) >> 3;
; #pragma unroll
;                         for (int e2 = 0; e2 < 4; ++e2) { p1[e2] = ror1(a[e2]); p2[e2] = ror2(a[e2]); }
;                         if (t < 2) { const f32x4 h1 = *(const f32x4*)(state_conv + ((size_t)bb * 2 + 1) * FF + j0 + 4 * n);
;                             if (t == 0) { p1 = h1; p2 = *(const f32x4*)(state_conv + ((size_t)bb * 2) * FF + j0 + 4 * n); } else p2 = h1; }
;                         if (t >= 6) *(f32x4*)(o_conv_s + ((size_t)bb * 2 + (t - 6)) * FF + j0 + 4 * n) = a;
;                     }
;                     f32x4 hv;
; #pragma unroll
;                     for (int e2 = 0; e2 < 1; ++e2) {
;                         const f32x4 c4 = cb + w0 * p2 + w1 * p1 + w2 * a;
;                         const f32x4 z = c4 * ((c4 * c4) * (-0.10294324f) + (-2.3022082f));
;                         f32x4 den; den[0] = 1.f + __builtin_amdgcn_exp2f(z[0]); den[1] = 1.f + __builtin_amdgcn_exp2f(z[1]); den[2] = 1.f + __builtin_amdgcn_exp2f(z[2]); den[3] = 1.f + __builtin_amdgcn_exp2f(z[3]);
;                         f32x4 rc; rc[0] = frcp(den[0]); rc[1] = frcp(den[1]); rc[2] = frcp(den[2]); rc[3] = frcp(den[3]);
;                         hv = (c4 * rc) * b; }
	v_add_f32_e32 v92, 1.0, v92
	v_add_f32_e32 v93, 1.0, v93
	v_rcp_f32_e32 v86, v86
	v_rcp_f32_e32 v87, v87
	v_rcp_f32_e32 v92, v92
	v_rcp_f32_e32 v93, v93
	s_nop 0
	v_mul_f32_e32 v208, v208, v86
	v_mul_f32_e32 v209, v209, v87
	v_mul_f32_e32 v210, v210, v92
	v_mul_f32_e32 v211, v211, v93
	v_cvt_pk_bf16_f32 v128, v208, v209
	v_cvt_pk_bf16_f32 v129, v210, v211
	v_fma_f32 v208, v46, v204, v230
	v_fma_f32 v209, v47, v205, v231
	v_fma_f32 v210, v48, v206, v232
	v_fma_f32 v211, v49, v207, v233
	v_fmac_f32_dpp v208, v46, v246 row_shr:1 row_mask:0xf bank_mask:0xf
	v_fmac_f32_dpp v209, v47, v247 row_shr:1 row_mask:0xf bank_mask:0xf
	v_fmac_f32_dpp v210, v48, v248 row_shr:1 row_mask:0xf bank_mask:0xf
	v_fmac_f32_dpp v211, v49, v249 row_shr:1 row_mask:0xf bank_mask:0xf
	v_fmac_f32_dpp v208, v46, v238 row_shr:2 row_mask:0xf bank_mask:0xf
	v_fmac_f32_dpp v209, v47, v239 row_shr:2 row_mask:0xf bank_mask:0xf
	v_fmac_f32_dpp v210, v48, v240 row_shr:2 row_mask:0xf bank_mask:0xf
	v_fmac_f32_dpp v211, v49, v241 row_shr:2 row_mask:0xf bank_mask:0xf
	v_fmac_f32_dpp v208, v54, v108 row_ror:1 row_mask:0xf bank_mask:0xf
	v_fmac_f32_dpp v209, v55, v109 row_ror:1 row_mask:0xf bank_mask:0xf
	v_fmac_f32_dpp v210, v56, v110 row_ror:1 row_mask:0xf bank_mask:0xf
	v_fmac_f32_dpp v211, v57, v111 row_ror:1 row_mask:0xf bank_mask:0xf
	v_fmac_f32_dpp v208, v54, v116 row_ror:2 row_mask:0xf bank_mask:0xf
	v_fmac_f32_dpp v209, v55, v117 row_ror:2 row_mask:0xf bank_mask:0xf
	v_fmac_f32_dpp v210, v56, v118 row_ror:2 row_mask:0xf bank_mask:0xf
	v_fmac_f32_dpp v211, v57, v119 row_ror:2 row_mask:0xf bank_mask:0xf
	v_mul_f32_e32 v86, v208, v208
	v_mul_f32_e32 v87, v209, v209
	v_mul_f32_e32 v92, v210, v210
	v_mul_f32_e32 v93, v211, v211
	v_fmamk_f32 v86, v86, 0xbdd2d3e8, v98
	v_fmamk_f32 v87, v87, 0xbdd2d3e8, v98
	v_fmamk_f32 v92, v92, 0xbdd2d3e8, v98
	v_fmamk_f32 v93, v93, 0xbdd2d3e8, v98
	v_mul_f32_e32 v86, v208, v86
	v_mul_f32_e32 v87, v209, v87
	v_mul_f32_e32 v92, v210, v92
	v_mul_f32_e32 v93, v211, v93
	v_exp_f32_e32 v86, v86
	v_exp_f32_e32 v87, v87
	v_exp_f32_e32 v92, v92
	v_exp_f32_e32 v93, v93
	v_mul_f32_e32 v208, v208, v42
	v_mul_f32_e32 v209, v209, v43
	v_mul_f32_e32 v210, v210, v44
	v_mul_f32_e32 v211, v211, v45
	v_add_f32_e32 v86, 1.0, v86
	v_add_f32_e32 v87, 1.0, v87
	v_add_f32_e32 v92, 1.0, v92
	v_add_f32_e32 v93, 1.0, v93
	v_rcp_f32_e32 v86, v86
	v_rcp_f32_e32 v87, v87
	v_rcp_f32_e32 v92, v92
	v_rcp_f32_e32 v93, v93
	s_nop 0
	v_mul_f32_e32 v208, v208, v86
	v_mul_f32_e32 v209, v209, v87
	v_mul_f32_e32 v210, v210, v92
	v_mul_f32_e32 v211, v211, v93
	v_cvt_pk_bf16_f32 v130, v208, v209
	v_cvt_pk_bf16_f32 v131, v210, v211
	global_store_dwordx4 v212, v[128:131], s[80:81]
	s_add_u32 s80, s80, 0x16000
	s_addc_u32 s81, s81, 0
	v_fma_f32 v208, v124, v250, v226
	v_fma_f32 v209, v125, v251, v227
	v_fma_f32 v210, v126, v252, v228
	v_fma_f32 v211, v127, v253, v229
	v_fmac_f32_dpp v208, v124, v242 row_shr:1 row_mask:0xf bank_mask:0xf
	v_fmac_f32_dpp v209, v125, v243 row_shr:1 row_mask:0xf bank_mask:0xf
	v_fmac_f32_dpp v210, v126, v244 row_shr:1 row_mask:0xf bank_mask:0xf
	v_fmac_f32_dpp v211, v127, v245 row_shr:1 row_mask:0xf bank_mask:0xf
	v_fmac_f32_dpp v208, v124, v234 row_shr:2 row_mask:0xf bank_mask:0xf
	v_fmac_f32_dpp v209, v125, v235 row_shr:2 row_mask:0xf bank_mask:0xf
	v_fmac_f32_dpp v210, v126, v236 row_shr:2 row_mask:0xf bank_mask:0xf
	v_fmac_f32_dpp v211, v127, v237 row_shr:2 row_mask:0xf bank_mask:0xf
	v_fmac_f32_dpp v208, v132, v104 row_ror:1 row_mask:0xf bank_mask:0xf
	v_fmac_f32_dpp v209, v133, v105 row_ror:1 row_mask:0xf bank_mask:0xf
	v_fmac_f32_dpp v210, v134, v106 row_ror:1 row_mask:0xf bank_mask:0xf
	v_fmac_f32_dpp v211, v135, v107 row_ror:1 row_mask:0xf bank_mask:0xf
	v_fmac_f32_dpp v208, v132, v112 row_ror:2 row_mask:0xf bank_mask:0xf
	v_fmac_f32_dpp v209, v133, v113 row_ror:2 row_mask:0xf bank_mask:0xf
	v_fmac_f32_dpp v210, v134, v114 row_ror:2 row_mask:0xf bank_mask:0xf
	v_fmac_f32_dpp v211, v135, v115 row_ror:2 row_mask:0xf bank_mask:0xf
	v_mul_f32_e32 v86, v208, v208
	v_mul_f32_e32 v87, v209, v209
	v_mul_f32_e32 v92, v210, v210
	v_mul_f32_e32 v93, v211, v211
	v_fmamk_f32 v86, v86, 0xbdd2d3e8, v98
	v_fmamk_f32 v87, v87, 0xbdd2d3e8, v98
	v_fmamk_f32 v92, v92, 0xbdd2d3e8, v98
	v_fmamk_f32 v93, v93, 0xbdd2d3e8, v98
	v_mul_f32_e32 v86, v208, v86
	v_mul_f32_e32 v87, v209, v87
	v_mul_f32_e32 v92, v210, v92
	v_mul_f32_e32 v93, v211, v93
	v_exp_f32_e32 v86, v86
	v_exp_f32_e32 v87, v87
	v_exp_f32_e32 v92, v92
	v_exp_f32_e32 v93, v93
	v_mul_f32_e32 v208, v208, v94
	v_mul_f32_e32 v209, v209, v95
	v_mul_f32_e32 v210, v210, v96
	v_mul_f32_e32 v211, v211, v97
	v_add_f32_e32 v86, 1.0, v86
	v_add_f32_e32 v87, 1.0, v87
	v_add_f32_e32 v92, 1.0, v92
	v_add_f32_e32 v93, 1.0, v93
	v_rcp_f32_e32 v86, v86
	v_rcp_f32_e32 v87, v87
	v_rcp_f32_e32 v92, v92
	v_rcp_f32_e32 v93, v93
	s_nop 0
	v_mul_f32_e32 v208, v208, v86
	v_mul_f32_e32 v209, v209, v87
	v_mul_f32_e32 v210, v210, v92
	v_mul_f32_e32 v211, v211, v93
	v_cvt_pk_bf16_f32 v94, v208, v209
	v_cvt_pk_bf16_f32 v95, v210, v211
	v_fma_f32 v208, v38, v204, v230
	v_fma_f32 v209, v39, v205, v231
	v_fma_f32 v210, v40, v206, v232
	v_fma_f32 v211, v41, v207, v233
	v_fmac_f32_dpp v208, v38, v246 row_shr:1 row_mask:0xf bank_mask:0xf
	v_fmac_f32_dpp v209, v39, v247 row_shr:1 row_mask:0xf bank_mask:0xf
	v_fmac_f32_dpp v210, v40, v248 row_shr:1 row_mask:0xf bank_mask:0xf
	v_fmac_f32_dpp v211, v41, v249 row_shr:1 row_mask:0xf bank_mask:0xf
	v_fmac_f32_dpp v208, v38, v238 row_shr:2 row_mask:0xf bank_mask:0xf
	v_fmac_f32_dpp v209, v39, v239 row_shr:2 row_mask:0xf bank_mask:0xf
	v_fmac_f32_dpp v210, v40, v240 row_shr:2 row_mask:0xf bank_mask:0xf
;     __device__ __forceinline__ void operator()(const f32x4 (&acc)[2][2][4][2], const Unit& u, int wr, int wc, int fr, int fq) const {
;     ...
;                 for (int m = 0; m < 4; ++m) {
;                     const int r = row0 + ai * HALF + m * 16; const float rs = rstd[ai][m];
;                     const f32x4 a = acc[ai][0][m][n] * rs, b = acc[ai][1][m][n] * rs; f32x4 p1, p2;
;                     if (!smp) {
; #pragma unroll
;                         for (int e2 = 0; e2 < 4; ++e2) { const float s1 = fr == 15 ? pa[e2] : a[e2], s2 = fr >= 14 ? pa[e2] : a[e2]; p1[e2] = ror1(s1); p2[e2] = ror2(s2); }
;                         if (ai == 0 && wr == 0 && m == 0 && fr < 2) { *(f32x4*)(EA + ((size_t)u.pm * 4 + fr) * FF + j0 + 4 * n) = a; *(f32x4*)(EB + ((size_t)u.pm * 2 + fr) * FF + j0 + 4 * n) = b; }
;                         if (ai == 1 && wr == 1 && m == 3 && fr >= 14) { *(f32x4*)(EA + ((size_t)u.pm * 4 + 2 + (fr - 14)) * FF + j0 + 4 * n) = a;
;                             if ((u.pm & 7) == 7) *(f32x4*)(o_conv_p + ((size_t)(u.pm >> 3) * 2 + (fr - 14)) * FF + j0 + 4 * n) = a; }
;                     } else {
;                         const int t = fr & 7, bb = (r - 16384) >> 3;
; #pragma unroll
;                         for (int e2 = 0; e2 < 4; ++e2) { p1[e2] = ror1(a[e2]); p2[e2] = ror2(a[e2]); }
;                         if (t < 2) { const f32x4 h1 = *(const f32x4*)(state_conv + ((size_t)bb * 2 + 1) * FF + j0 + 4 * n);
;                             if (t == 0) { p1 = h1; p2 = *(const f32x4*)(state_conv + ((size_t)bb * 2) * FF + j0 + 4 * n); } else p2 = h1; }
;                         if (t >= 6) *(f32x4*)(o_conv_s + ((size_t)bb * 2 + (t - 6)) * FF + j0 + 4 * n) = a;
;                     }
;                     f32x4 hv;
; #pragma unroll
;                     for (int e2 = 0; e2 < 1; ++e2) {
;                         const f32x4 c4 = cb + w0 * p2 + w1 * p1 + w2 * a;
;                         const f32x4 z = c4 * ((c4 * c4) * (-0.10294324f) + (-2.3022082f));
;                         f32x4 den; den[0] = 1.f + __builtin_amdgcn_exp2f(z[0]); den[1] = 1.f + __builtin_amdgcn_exp2f(z[1]); den[2] = 1.f + __builtin_amdgcn_exp2f(z[2]); den[3] = 1.f + __builtin_amdgcn_exp2f(z[3]);
;                         f32x4 rc; rc[0] = frcp(den[0]); rc[1] = frcp(den[1]); rc[2] = frcp(den[2]); rc[3] = frcp(den[3]);
;                         hv = (c4 * rc) * b; }
	v_fmac_f32_dpp v211, v41, v241 row_shr:2 row_mask:0xf bank_mask:0xf
	v_fmac_f32_dpp v208, v46, v108 row_ror:1 row_mask:0xf bank_mask:0xf
	v_fmac_f32_dpp v209, v47, v109 row_ror:1 row_mask:0xf bank_mask:0xf
	v_fmac_f32_dpp v210, v48, v110 row_ror:1 row_mask:0xf bank_mask:0xf
	v_fmac_f32_dpp v211, v49, v111 row_ror:1 row_mask:0xf bank_mask:0xf
	v_fmac_f32_dpp v208, v46, v116 row_ror:2 row_mask:0xf bank_mask:0xf
	v_fmac_f32_dpp v209, v47, v117 row_ror:2 row_mask:0xf bank_mask:0xf
	v_fmac_f32_dpp v210, v48, v118 row_ror:2 row_mask:0xf bank_mask:0xf
	v_fmac_f32_dpp v211, v49, v119 row_ror:2 row_mask:0xf bank_mask:0xf
	v_mul_f32_e32 v86, v208, v208
	v_mul_f32_e32 v87, v209, v209
	v_mul_f32_e32 v92, v210, v210
	v_mul_f32_e32 v93, v211, v211
	v_fmamk_f32 v86, v86, 0xbdd2d3e8, v98
	v_fmamk_f32 v87, v87, 0xbdd2d3e8, v98
	v_fmamk_f32 v92, v92, 0xbdd2d3e8, v98
	v_fmamk_f32 v93, v93, 0xbdd2d3e8, v98
	v_mul_f32_e32 v86, v208, v86
	v_mul_f32_e32 v87, v209, v87
	v_mul_f32_e32 v92, v210, v92
	v_mul_f32_e32 v93, v211, v93
	v_exp_f32_e32 v86, v86
	v_exp_f32_e32 v87, v87
	v_exp_f32_e32 v92, v92
	v_exp_f32_e32 v93, v93
	v_mul_f32_e32 v208, v208, v34
	v_mul_f32_e32 v209, v209, v35
	v_mul_f32_e32 v210, v210, v36
	v_mul_f32_e32 v211, v211, v37
	v_add_f32_e32 v86, 1.0, v86
	v_add_f32_e32 v87, 1.0, v87
	v_add_f32_e32 v92, 1.0, v92
	v_add_f32_e32 v93, 1.0, v93
	v_rcp_f32_e32 v86, v86
	v_rcp_f32_e32 v87, v87
	v_rcp_f32_e32 v92, v92
	v_rcp_f32_e32 v93, v93
	s_nop 0
	v_mul_f32_e32 v208, v208, v86
	v_mul_f32_e32 v209, v209, v87
	v_mul_f32_e32 v210, v210, v92
	v_mul_f32_e32 v211, v211, v93
	v_cvt_pk_bf16_f32 v96, v208, v209
	v_cvt_pk_bf16_f32 v97, v210, v211
	global_store_dwordx4 v212, v[94:97], s[80:81]
	s_add_u32 s80, s80, 0x6e000
	s_addc_u32 s81, s81, 0
	v_fma_f32 v208, v120, v250, v226
	v_fma_f32 v209, v121, v251, v227
	v_fma_f32 v210, v122, v252, v228
	v_fma_f32 v211, v123, v253, v229
	v_fmac_f32_dpp v208, v120, v242 row_shr:1 row_mask:0xf bank_mask:0xf
	v_fmac_f32_dpp v209, v121, v243 row_shr:1 row_mask:0xf bank_mask:0xf
	v_fmac_f32_dpp v210, v122, v244 row_shr:1 row_mask:0xf bank_mask:0xf
	v_fmac_f32_dpp v211, v123, v245 row_shr:1 row_mask:0xf bank_mask:0xf
	v_fmac_f32_dpp v208, v120, v234 row_shr:2 row_mask:0xf bank_mask:0xf
	v_fmac_f32_dpp v209, v121, v235 row_shr:2 row_mask:0xf bank_mask:0xf
	v_fmac_f32_dpp v210, v122, v236 row_shr:2 row_mask:0xf bank_mask:0xf
	v_fmac_f32_dpp v211, v123, v237 row_shr:2 row_mask:0xf bank_mask:0xf
	v_fmac_f32_dpp v208, v196, v104 row_ror:1 row_mask:0xf bank_mask:0xf
	v_fmac_f32_dpp v209, v197, v105 row_ror:1 row_mask:0xf bank_mask:0xf
	v_fmac_f32_dpp v210, v198, v106 row_ror:1 row_mask:0xf bank_mask:0xf
	v_fmac_f32_dpp v211, v199, v107 row_ror:1 row_mask:0xf bank_mask:0xf
	v_fmac_f32_dpp v208, v196, v112 row_ror:2 row_mask:0xf bank_mask:0xf
	v_fmac_f32_dpp v209, v197, v113 row_ror:2 row_mask:0xf bank_mask:0xf
	v_fmac_f32_dpp v210, v198, v114 row_ror:2 row_mask:0xf bank_mask:0xf
	v_fmac_f32_dpp v211, v199, v115 row_ror:2 row_mask:0xf bank_mask:0xf
	v_mul_f32_e32 v86, v208, v208
	v_mul_f32_e32 v87, v209, v209
	v_mul_f32_e32 v92, v210, v210
	v_mul_f32_e32 v93, v211, v211
	v_fmamk_f32 v86, v86, 0xbdd2d3e8, v98
	v_fmamk_f32 v87, v87, 0xbdd2d3e8, v98
	v_fmamk_f32 v92, v92, 0xbdd2d3e8, v98
	v_fmamk_f32 v93, v93, 0xbdd2d3e8, v98
	v_mul_f32_e32 v86, v208, v86
	v_mul_f32_e32 v87, v209, v87
	v_mul_f32_e32 v92, v210, v92
	v_mul_f32_e32 v93, v211, v93
	v_exp_f32_e32 v86, v86
	v_exp_f32_e32 v87, v87
	v_exp_f32_e32 v92, v92
	v_exp_f32_e32 v93, v93
	v_mul_f32_e32 v208, v208, v100
	v_mul_f32_e32 v209, v209, v101
	v_mul_f32_e32 v210, v210, v102
	v_mul_f32_e32 v211, v211, v103
	v_add_f32_e32 v86, 1.0, v86
	v_add_f32_e32 v87, 1.0, v87
	v_add_f32_e32 v92, 1.0, v92
	v_add_f32_e32 v93, 1.0, v93
	v_rcp_f32_e32 v86, v86
	v_rcp_f32_e32 v87, v87
	v_rcp_f32_e32 v92, v92
	v_rcp_f32_e32 v93, v93
	s_nop 0
	v_mul_f32_e32 v208, v208, v86
	v_mul_f32_e32 v209, v209, v87
	v_mul_f32_e32 v210, v210, v92
	v_mul_f32_e32 v211, v211, v93
	v_cvt_pk_bf16_f32 v100, v208, v209
	v_cvt_pk_bf16_f32 v101, v210, v211
	v_fma_f32 v208, v30, v204, v230
	v_fma_f32 v209, v31, v205, v231
	v_fma_f32 v210, v32, v206, v232
	v_fma_f32 v211, v33, v207, v233
	v_fmac_f32_dpp v208, v30, v246 row_shr:1 row_mask:0xf bank_mask:0xf
	v_fmac_f32_dpp v209, v31, v247 row_shr:1 row_mask:0xf bank_mask:0xf
	v_fmac_f32_dpp v210, v32, v248 row_shr:1 row_mask:0xf bank_mask:0xf
	v_fmac_f32_dpp v211, v33, v249 row_shr:1 row_mask:0xf bank_mask:0xf
	v_fmac_f32_dpp v208, v30, v238 row_shr:2 row_mask:0xf bank_mask:0xf
	v_fmac_f32_dpp v209, v31, v239 row_shr:2 row_mask:0xf bank_mask:0xf
	v_fmac_f32_dpp v210, v32, v240 row_shr:2 row_mask:0xf bank_mask:0xf
	v_fmac_f32_dpp v211, v33, v241 row_shr:2 row_mask:0xf bank_mask:0xf
	v_fmac_f32_dpp v208, v160, v108 row_ror:1 row_mask:0xf bank_mask:0xf
	v_fmac_f32_dpp v209, v161, v109 row_ror:1 row_mask:0xf bank_mask:0xf
	v_fmac_f32_dpp v210, v162, v110 row_ror:1 row_mask:0xf bank_mask:0xf
	v_fmac_f32_dpp v211, v163, v111 row_ror:1 row_mask:0xf bank_mask:0xf
	v_fmac_f32_dpp v208, v160, v116 row_ror:2 row_mask:0xf bank_mask:0xf
	v_fmac_f32_dpp v209, v161, v117 row_ror:2 row_mask:0xf bank_mask:0xf
	v_fmac_f32_dpp v210, v162, v118 row_ror:2 row_mask:0xf bank_mask:0xf
	v_fmac_f32_dpp v211, v163, v119 row_ror:2 row_mask:0xf bank_mask:0xf
	v_mul_f32_e32 v86, v208, v208
	v_mul_f32_e32 v87, v209, v209
	v_mul_f32_e32 v92, v210, v210
	v_mul_f32_e32 v93, v211, v211
	v_fmamk_f32 v86, v86, 0xbdd2d3e8, v98
	v_fmamk_f32 v87, v87, 0xbdd2d3e8, v98
	v_fmamk_f32 v92, v92, 0xbdd2d3e8, v98
	v_fmamk_f32 v93, v93, 0xbdd2d3e8, v98
	v_mul_f32_e32 v86, v208, v86
	v_mul_f32_e32 v87, v209, v87
;     __device__ __forceinline__ void operator()(const f32x4 (&acc)[2][2][4][2], const Unit& u, int wr, int wc, int fr, int fq) const {
;     ...
;                 for (int m = 0; m < 4; ++m) {
;                     const int r = row0 + ai * HALF + m * 16; const float rs = rstd[ai][m];
;                     const f32x4 a = acc[ai][0][m][n] * rs, b = acc[ai][1][m][n] * rs; f32x4 p1, p2;
;                     if (!smp) {
; #pragma unroll
;                         for (int e2 = 0; e2 < 4; ++e2) { const float s1 = fr == 15 ? pa[e2] : a[e2], s2 = fr >= 14 ? pa[e2] : a[e2]; p1[e2] = ror1(s1); p2[e2] = ror2(s2); }
;                         if (ai == 0 && wr == 0 && m == 0 && fr < 2) { *(f32x4*)(EA + ((size_t)u.pm * 4 + fr) * FF + j0 + 4 * n) = a; *(f32x4*)(EB + ((size_t)u.pm * 2 + fr) * FF + j0 + 4 * n) = b; }
;                         if (ai == 1 && wr == 1 && m == 3 && fr >= 14) { *(f32x4*)(EA + ((size_t)u.pm * 4 + 2 + (fr - 14)) * FF + j0 + 4 * n) = a;
;                             if ((u.pm & 7) == 7) *(f32x4*)(o_conv_p + ((size_t)(u.pm >> 3) * 2 + (fr - 14)) * FF + j0 + 4 * n) = a; }
;                     } else {
;                         const int t = fr & 7, bb = (r - 16384) >> 3;
; #pragma unroll
;                         for (int e2 = 0; e2 < 4; ++e2) { p1[e2] = ror1(a[e2]); p2[e2] = ror2(a[e2]); }
;                         if (t < 2) { const f32x4 h1 = *(const f32x4*)(state_conv + ((size_t)bb * 2 + 1) * FF + j0 + 4 * n);
;                             if (t == 0) { p1 = h1; p2 = *(const f32x4*)(state_conv + ((size_t)bb * 2) * FF + j0 + 4 * n); } else p2 = h1; }
;                         if (t >= 6) *(f32x4*)(o_conv_s + ((size_t)bb * 2 + (t - 6)) * FF + j0 + 4 * n) = a;
;                     }
;                     f32x4 hv;
; #pragma unroll
;                     for (int e2 = 0; e2 < 1; ++e2) {
;                         const f32x4 c4 = cb + w0 * p2 + w1 * p1 + w2 * a;
;                         const f32x4 z = c4 * ((c4 * c4) * (-0.10294324f) + (-2.3022082f));
;                         f32x4 den; den[0] = 1.f + __builtin_amdgcn_exp2f(z[0]); den[1] = 1.f + __builtin_amdgcn_exp2f(z[1]); den[2] = 1.f + __builtin_amdgcn_exp2f(z[2]); den[3] = 1.f + __builtin_amdgcn_exp2f(z[3]);
;                         f32x4 rc; rc[0] = frcp(den[0]); rc[1] = frcp(den[1]); rc[2] = frcp(den[2]); rc[3] = frcp(den[3]);
;                         hv = (c4 * rc) * b; }
	v_mul_f32_e32 v92, v210, v92
	v_mul_f32_e32 v93, v211, v93
	v_exp_f32_e32 v86, v86
	v_exp_f32_e32 v87, v87
	v_exp_f32_e32 v92, v92
	v_exp_f32_e32 v93, v93
	v_mul_f32_e32 v208, v208, v26
	v_mul_f32_e32 v209, v209, v27
	v_mul_f32_e32 v210, v210, v28
	v_mul_f32_e32 v211, v211, v29
	v_add_f32_e32 v86, 1.0, v86
	v_add_f32_e32 v87, 1.0, v87
	v_add_f32_e32 v92, 1.0, v92
	v_add_f32_e32 v93, 1.0, v93
	v_rcp_f32_e32 v86, v86
	v_rcp_f32_e32 v87, v87
	v_rcp_f32_e32 v92, v92
	v_rcp_f32_e32 v93, v93
	s_nop 0
	v_mul_f32_e32 v208, v208, v86
	v_mul_f32_e32 v209, v209, v87
	v_mul_f32_e32 v210, v210, v92
	v_mul_f32_e32 v211, v211, v93
	v_cvt_pk_bf16_f32 v102, v208, v209
	v_cvt_pk_bf16_f32 v103, v210, v211
	global_store_dwordx4 v212, v[100:103], s[80:81]
	s_add_u32 s80, s80, 0x16000
	s_addc_u32 s81, s81, 0
	v_fma_f32 v208, v88, v250, v226
	v_fma_f32 v209, v89, v251, v227
	v_fma_f32 v210, v90, v252, v228
	v_fma_f32 v211, v91, v253, v229
	v_fmac_f32_dpp v208, v88, v242 row_shr:1 row_mask:0xf bank_mask:0xf
	v_fmac_f32_dpp v209, v89, v243 row_shr:1 row_mask:0xf bank_mask:0xf
	v_fmac_f32_dpp v210, v90, v244 row_shr:1 row_mask:0xf bank_mask:0xf
	v_fmac_f32_dpp v211, v91, v245 row_shr:1 row_mask:0xf bank_mask:0xf
	v_fmac_f32_dpp v208, v88, v234 row_shr:2 row_mask:0xf bank_mask:0xf
	v_fmac_f32_dpp v209, v89, v235 row_shr:2 row_mask:0xf bank_mask:0xf
	v_fmac_f32_dpp v210, v90, v236 row_shr:2 row_mask:0xf bank_mask:0xf
	v_fmac_f32_dpp v211, v91, v237 row_shr:2 row_mask:0xf bank_mask:0xf
	v_fmac_f32_dpp v208, v120, v104 row_ror:1 row_mask:0xf bank_mask:0xf
	v_fmac_f32_dpp v209, v121, v105 row_ror:1 row_mask:0xf bank_mask:0xf
	v_fmac_f32_dpp v210, v122, v106 row_ror:1 row_mask:0xf bank_mask:0xf
	v_fmac_f32_dpp v211, v123, v107 row_ror:1 row_mask:0xf bank_mask:0xf
	v_fmac_f32_dpp v208, v120, v112 row_ror:2 row_mask:0xf bank_mask:0xf
	v_fmac_f32_dpp v209, v121, v113 row_ror:2 row_mask:0xf bank_mask:0xf
	v_fmac_f32_dpp v210, v122, v114 row_ror:2 row_mask:0xf bank_mask:0xf
	v_fmac_f32_dpp v211, v123, v115 row_ror:2 row_mask:0xf bank_mask:0xf
	v_mul_f32_e32 v86, v208, v208
	v_mul_f32_e32 v87, v209, v209
	v_mul_f32_e32 v92, v210, v210
	v_mul_f32_e32 v93, v211, v211
	v_fmamk_f32 v86, v86, 0xbdd2d3e8, v98
	v_fmamk_f32 v87, v87, 0xbdd2d3e8, v98
	v_fmamk_f32 v92, v92, 0xbdd2d3e8, v98
	v_fmamk_f32 v93, v93, 0xbdd2d3e8, v98
	v_mul_f32_e32 v86, v208, v86
	v_mul_f32_e32 v87, v209, v87
	v_mul_f32_e32 v92, v210, v92
	v_mul_f32_e32 v93, v211, v93
	v_exp_f32_e32 v86, v86
	v_exp_f32_e32 v87, v87
	v_exp_f32_e32 v92, v92
	v_exp_f32_e32 v93, v93
	v_mul_f32_e32 v208, v208, v82
	v_mul_f32_e32 v209, v209, v83
	v_mul_f32_e32 v210, v210, v84
	v_mul_f32_e32 v211, v211, v85
	v_add_f32_e32 v86, 1.0, v86
	v_add_f32_e32 v87, 1.0, v87
	v_add_f32_e32 v92, 1.0, v92
	v_add_f32_e32 v93, 1.0, v93
	v_rcp_f32_e32 v86, v86
	v_rcp_f32_e32 v87, v87
	v_rcp_f32_e32 v92, v92
	v_rcp_f32_e32 v93, v93
	s_nop 0
	v_mul_f32_e32 v208, v208, v86
	v_mul_f32_e32 v209, v209, v87
	v_mul_f32_e32 v210, v210, v92
	v_mul_f32_e32 v211, v211, v93
	v_cvt_pk_bf16_f32 v82, v208, v209
	v_cvt_pk_bf16_f32 v83, v210, v211
	v_fma_f32 v208, v22, v204, v230
	v_fma_f32 v209, v23, v205, v231
	v_fma_f32 v210, v24, v206, v232
	v_fma_f32 v211, v25, v207, v233
	v_fmac_f32_dpp v208, v22, v246 row_shr:1 row_mask:0xf bank_mask:0xf
	v_fmac_f32_dpp v209, v23, v247 row_shr:1 row_mask:0xf bank_mask:0xf
	v_fmac_f32_dpp v210, v24, v248 row_shr:1 row_mask:0xf bank_mask:0xf
	v_fmac_f32_dpp v211, v25, v249 row_shr:1 row_mask:0xf bank_mask:0xf
	v_fmac_f32_dpp v208, v22, v238 row_shr:2 row_mask:0xf bank_mask:0xf
	v_fmac_f32_dpp v209, v23, v239 row_shr:2 row_mask:0xf bank_mask:0xf
	v_fmac_f32_dpp v210, v24, v240 row_shr:2 row_mask:0xf bank_mask:0xf
	v_fmac_f32_dpp v211, v25, v241 row_shr:2 row_mask:0xf bank_mask:0xf
	v_fmac_f32_dpp v208, v30, v108 row_ror:1 row_mask:0xf bank_mask:0xf
	v_fmac_f32_dpp v209, v31, v109 row_ror:1 row_mask:0xf bank_mask:0xf
	v_fmac_f32_dpp v210, v32, v110 row_ror:1 row_mask:0xf bank_mask:0xf
	v_fmac_f32_dpp v211, v33, v111 row_ror:1 row_mask:0xf bank_mask:0xf
	v_fmac_f32_dpp v208, v30, v116 row_ror:2 row_mask:0xf bank_mask:0xf
	v_fmac_f32_dpp v209, v31, v117 row_ror:2 row_mask:0xf bank_mask:0xf
	v_fmac_f32_dpp v210, v32, v118 row_ror:2 row_mask:0xf bank_mask:0xf
	v_fmac_f32_dpp v211, v33, v119 row_ror:2 row_mask:0xf bank_mask:0xf
	v_mul_f32_e32 v86, v208, v208
	v_mul_f32_e32 v87, v209, v209
	v_mul_f32_e32 v92, v210, v210
	v_mul_f32_e32 v93, v211, v211
	v_fmamk_f32 v86, v86, 0xbdd2d3e8, v98
	v_fmamk_f32 v87, v87, 0xbdd2d3e8, v98
	v_fmamk_f32 v92, v92, 0xbdd2d3e8, v98
	v_fmamk_f32 v93, v93, 0xbdd2d3e8, v98
	v_mul_f32_e32 v86, v208, v86
	v_mul_f32_e32 v87, v209, v87
	v_mul_f32_e32 v92, v210, v92
	v_mul_f32_e32 v93, v211, v93
	v_exp_f32_e32 v86, v86
	v_exp_f32_e32 v87, v87
	v_exp_f32_e32 v92, v92
	v_exp_f32_e32 v93, v93
	v_mul_f32_e32 v208, v208, v18
	v_mul_f32_e32 v209, v209, v19
	v_mul_f32_e32 v210, v210, v20
	v_mul_f32_e32 v211, v211, v21
	v_add_f32_e32 v86, 1.0, v86
	v_add_f32_e32 v87, 1.0, v87
	v_add_f32_e32 v92, 1.0, v92
	v_add_f32_e32 v93, 1.0, v93
	v_rcp_f32_e32 v86, v86
	v_rcp_f32_e32 v87, v87
	v_rcp_f32_e32 v92, v92
	v_rcp_f32_e32 v93, v93
	s_nop 0
	v_mul_f32_e32 v208, v208, v86
	v_mul_f32_e32 v209, v209, v87
	v_mul_f32_e32 v210, v210, v92
	v_mul_f32_e32 v211, v211, v93
	v_cvt_pk_bf16_f32 v84, v208, v209
	v_cvt_pk_bf16_f32 v85, v210, v211
	global_store_dwordx4 v212, v[82:85], s[80:81]
	s_add_u32 s80, s80, 0x16000
	s_addc_u32 s81, s81, 0
	v_fma_f32 v208, v78, v250, v226
	v_fma_f32 v209, v79, v251, v227
	v_fma_f32 v210, v80, v252, v228
	v_fma_f32 v211, v81, v253, v229
	v_fmac_f32_dpp v208, v78, v242 row_shr:1 row_mask:0xf bank_mask:0xf
;     __device__ __forceinline__ void operator()(const f32x4 (&acc)[2][2][4][2], const Unit& u, int wr, int wc, int fr, int fq) const {
;     ...
;                 for (int m = 0; m < 4; ++m) {
;                     const int r = row0 + ai * HALF + m * 16; const float rs = rstd[ai][m];
;                     const f32x4 a = acc[ai][0][m][n] * rs, b = acc[ai][1][m][n] * rs; f32x4 p1, p2;
;                     if (!smp) {
; #pragma unroll
;                         for (int e2 = 0; e2 < 4; ++e2) { const float s1 = fr == 15 ? pa[e2] : a[e2], s2 = fr >= 14 ? pa[e2] : a[e2]; p1[e2] = ror1(s1); p2[e2] = ror2(s2); }
;                         if (ai == 0 && wr == 0 && m == 0 && fr < 2) { *(f32x4*)(EA + ((size_t)u.pm * 4 + fr) * FF + j0 + 4 * n) = a; *(f32x4*)(EB + ((size_t)u.pm * 2 + fr) * FF + j0 + 4 * n) = b; }
;                         if (ai == 1 && wr == 1 && m == 3 && fr >= 14) { *(f32x4*)(EA + ((size_t)u.pm * 4 + 2 + (fr - 14)) * FF + j0 + 4 * n) = a;
;                             if ((u.pm & 7) == 7) *(f32x4*)(o_conv_p + ((size_t)(u.pm >> 3) * 2 + (fr - 14)) * FF + j0 + 4 * n) = a; }
;                     } else {
;                         const int t = fr & 7, bb = (r - 16384) >> 3;
; #pragma unroll
;                         for (int e2 = 0; e2 < 4; ++e2) { p1[e2] = ror1(a[e2]); p2[e2] = ror2(a[e2]); }
;                         if (t < 2) { const f32x4 h1 = *(const f32x4*)(state_conv + ((size_t)bb * 2 + 1) * FF + j0 + 4 * n);
;                             if (t == 0) { p1 = h1; p2 = *(const f32x4*)(state_conv + ((size_t)bb * 2) * FF + j0 + 4 * n); } else p2 = h1; }
;                         if (t >= 6) *(f32x4*)(o_conv_s + ((size_t)bb * 2 + (t - 6)) * FF + j0 + 4 * n) = a;
;                     }
;                     f32x4 hv;
; #pragma unroll
;                     for (int e2 = 0; e2 < 1; ++e2) {
;                         const f32x4 c4 = cb + w0 * p2 + w1 * p1 + w2 * a;
;                         const f32x4 z = c4 * ((c4 * c4) * (-0.10294324f) + (-2.3022082f));
;                         f32x4 den; den[0] = 1.f + __builtin_amdgcn_exp2f(z[0]); den[1] = 1.f + __builtin_amdgcn_exp2f(z[1]); den[2] = 1.f + __builtin_amdgcn_exp2f(z[2]); den[3] = 1.f + __builtin_amdgcn_exp2f(z[3]);
;                         f32x4 rc; rc[0] = frcp(den[0]); rc[1] = frcp(den[1]); rc[2] = frcp(den[2]); rc[3] = frcp(den[3]);
;                         hv = (c4 * rc) * b; }
	v_fmac_f32_dpp v209, v79, v243 row_shr:1 row_mask:0xf bank_mask:0xf
	v_fmac_f32_dpp v210, v80, v244 row_shr:1 row_mask:0xf bank_mask:0xf
	v_fmac_f32_dpp v211, v81, v245 row_shr:1 row_mask:0xf bank_mask:0xf
	v_fmac_f32_dpp v208, v78, v234 row_shr:2 row_mask:0xf bank_mask:0xf
	v_fmac_f32_dpp v209, v79, v235 row_shr:2 row_mask:0xf bank_mask:0xf
	v_fmac_f32_dpp v210, v80, v236 row_shr:2 row_mask:0xf bank_mask:0xf
	v_fmac_f32_dpp v211, v81, v237 row_shr:2 row_mask:0xf bank_mask:0xf
	v_fmac_f32_dpp v208, v88, v104 row_ror:1 row_mask:0xf bank_mask:0xf
	v_fmac_f32_dpp v209, v89, v105 row_ror:1 row_mask:0xf bank_mask:0xf
	v_fmac_f32_dpp v210, v90, v106 row_ror:1 row_mask:0xf bank_mask:0xf
	v_fmac_f32_dpp v211, v91, v107 row_ror:1 row_mask:0xf bank_mask:0xf
	v_fmac_f32_dpp v208, v88, v112 row_ror:2 row_mask:0xf bank_mask:0xf
	v_fmac_f32_dpp v209, v89, v113 row_ror:2 row_mask:0xf bank_mask:0xf
	v_fmac_f32_dpp v210, v90, v114 row_ror:2 row_mask:0xf bank_mask:0xf
	v_fmac_f32_dpp v211, v91, v115 row_ror:2 row_mask:0xf bank_mask:0xf
	v_mul_f32_e32 v86, v208, v208
	v_mul_f32_e32 v87, v209, v209
	v_mul_f32_e32 v92, v210, v210
	v_mul_f32_e32 v93, v211, v211
	v_fmamk_f32 v86, v86, 0xbdd2d3e8, v98
	v_fmamk_f32 v87, v87, 0xbdd2d3e8, v98
	v_fmamk_f32 v92, v92, 0xbdd2d3e8, v98
	v_fmamk_f32 v93, v93, 0xbdd2d3e8, v98
	v_mul_f32_e32 v86, v208, v86
	v_mul_f32_e32 v87, v209, v87
	v_mul_f32_e32 v92, v210, v92
	v_mul_f32_e32 v93, v211, v93
	v_exp_f32_e32 v86, v86
	v_exp_f32_e32 v87, v87
	v_exp_f32_e32 v92, v92
	v_exp_f32_e32 v93, v93
	v_mul_f32_e32 v208, v208, v70
	v_mul_f32_e32 v209, v209, v71
	v_mul_f32_e32 v210, v210, v72
	v_mul_f32_e32 v211, v211, v73
	v_add_f32_e32 v86, 1.0, v86
	v_add_f32_e32 v87, 1.0, v87
	v_add_f32_e32 v92, 1.0, v92
	v_add_f32_e32 v93, 1.0, v93
	v_rcp_f32_e32 v86, v86
	v_rcp_f32_e32 v87, v87
	v_rcp_f32_e32 v92, v92
	v_rcp_f32_e32 v93, v93
	s_nop 0
	v_mul_f32_e32 v208, v208, v86
	v_mul_f32_e32 v209, v209, v87
	v_mul_f32_e32 v210, v210, v92
	v_mul_f32_e32 v211, v211, v93
	v_cvt_pk_bf16_f32 v70, v208, v209
	v_cvt_pk_bf16_f32 v71, v210, v211
	v_fma_f32 v208, v14, v204, v230
	v_fma_f32 v209, v15, v205, v231
	v_fma_f32 v210, v16, v206, v232
	v_fma_f32 v211, v17, v207, v233
	v_fmac_f32_dpp v208, v14, v246 row_shr:1 row_mask:0xf bank_mask:0xf
	v_fmac_f32_dpp v209, v15, v247 row_shr:1 row_mask:0xf bank_mask:0xf
	v_fmac_f32_dpp v210, v16, v248 row_shr:1 row_mask:0xf bank_mask:0xf
	v_fmac_f32_dpp v211, v17, v249 row_shr:1 row_mask:0xf bank_mask:0xf
	v_fmac_f32_dpp v208, v14, v238 row_shr:2 row_mask:0xf bank_mask:0xf
	v_fmac_f32_dpp v209, v15, v239 row_shr:2 row_mask:0xf bank_mask:0xf
	v_fmac_f32_dpp v210, v16, v240 row_shr:2 row_mask:0xf bank_mask:0xf
	v_fmac_f32_dpp v211, v17, v241 row_shr:2 row_mask:0xf bank_mask:0xf
	v_fmac_f32_dpp v208, v22, v108 row_ror:1 row_mask:0xf bank_mask:0xf
	v_fmac_f32_dpp v209, v23, v109 row_ror:1 row_mask:0xf bank_mask:0xf
	v_fmac_f32_dpp v210, v24, v110 row_ror:1 row_mask:0xf bank_mask:0xf
	v_fmac_f32_dpp v211, v25, v111 row_ror:1 row_mask:0xf bank_mask:0xf
	v_fmac_f32_dpp v208, v22, v116 row_ror:2 row_mask:0xf bank_mask:0xf
	v_fmac_f32_dpp v209, v23, v117 row_ror:2 row_mask:0xf bank_mask:0xf
	v_fmac_f32_dpp v210, v24, v118 row_ror:2 row_mask:0xf bank_mask:0xf
	v_fmac_f32_dpp v211, v25, v119 row_ror:2 row_mask:0xf bank_mask:0xf
	v_mul_f32_e32 v86, v208, v208
	v_mul_f32_e32 v87, v209, v209
	v_mul_f32_e32 v92, v210, v210
	v_mul_f32_e32 v93, v211, v211
	v_fmamk_f32 v86, v86, 0xbdd2d3e8, v98
	v_fmamk_f32 v87, v87, 0xbdd2d3e8, v98
	v_fmamk_f32 v92, v92, 0xbdd2d3e8, v98
	v_fmamk_f32 v93, v93, 0xbdd2d3e8, v98
	v_mul_f32_e32 v86, v208, v86
	v_mul_f32_e32 v87, v209, v87
	v_mul_f32_e32 v92, v210, v92
	v_mul_f32_e32 v93, v211, v93
	v_exp_f32_e32 v86, v86
	v_exp_f32_e32 v87, v87
	v_exp_f32_e32 v92, v92
	v_exp_f32_e32 v93, v93
	v_mul_f32_e32 v208, v208, v10
	v_mul_f32_e32 v209, v209, v11
	v_mul_f32_e32 v210, v210, v12
	v_mul_f32_e32 v211, v211, v13
	v_add_f32_e32 v86, 1.0, v86
	v_add_f32_e32 v87, 1.0, v87
	v_add_f32_e32 v92, 1.0, v92
	v_add_f32_e32 v93, 1.0, v93
	v_rcp_f32_e32 v86, v86
	v_rcp_f32_e32 v87, v87
	v_rcp_f32_e32 v92, v92
	v_rcp_f32_e32 v93, v93
	s_nop 0
	v_mul_f32_e32 v208, v208, v86
	v_mul_f32_e32 v209, v209, v87
	v_mul_f32_e32 v210, v210, v92
	v_mul_f32_e32 v211, v211, v93
	v_cvt_pk_bf16_f32 v72, v208, v209
	v_cvt_pk_bf16_f32 v73, v210, v211
	global_store_dwordx4 v212, v[70:73], s[80:81]
	s_add_u32 s80, s80, 0x16000
	s_addc_u32 s81, s81, 0
	s_cmp_lg_u32 s71, 1
	s_cbranch_scc1 .Lepi5_noedge1
	v_add_u32_e32 v99, -14, v200
	s_movk_i32 s75, 0x2c00
	v_mad_u32_u24 v99, v99, s75, v213
	s_mul_i32 s73, s28, 0xb000
	s_add_u32 s73, s73, 0x5800
	s_add_u32 s88, s86, 0x4000000
	s_addc_u32 s89, s87, 0
	s_add_u32 s88, s88, s73
	s_addc_u32 s89, s89, 0
	s_mov_b64 exec, s[90:91]
	global_store_dwordx4 v99, v[74:77], s[88:89]
	global_store_dwordx4 v99, v[6:9], s[88:89] offset:16
	s_and_b32 s73, s28, 7
	s_cmp_lg_u32 s73, 7
	s_cbranch_scc1 .Lepi5_noconvp
	v_readlane_b32 s88, v254, 58
	v_readlane_b32 s89, v254, 59
	s_lshr_b32 s73, s28, 3
	s_mul_i32 s73, s73, 0x5800
	s_add_u32 s73, s73, 0x461e000
	s_nop 4
	s_add_u32 s88, s88, s73
	s_addc_u32 s89, s89, 0
	global_store_dwordx4 v99, v[74:77], s[88:89]
	global_store_dwordx4 v99, v[6:9], s[88:89] offset:16
;     __device__ __forceinline__ void operator()(const f32x4 (&acc)[2][2][4][2], const Unit& u, int wr, int wc, int fr, int fq) const {
;     ...
;                 for (int m = 0; m < 4; ++m) {
;                     const int r = row0 + ai * HALF + m * 16; const float rs = rstd[ai][m];
;                     const f32x4 a = acc[ai][0][m][n] * rs, b = acc[ai][1][m][n] * rs; f32x4 p1, p2;
;                     if (!smp) {
; #pragma unroll
;                         for (int e2 = 0; e2 < 4; ++e2) { const float s1 = fr == 15 ? pa[e2] : a[e2], s2 = fr >= 14 ? pa[e2] : a[e2]; p1[e2] = ror1(s1); p2[e2] = ror2(s2); }
;                         if (ai == 0 && wr == 0 && m == 0 && fr < 2) { *(f32x4*)(EA + ((size_t)u.pm * 4 + fr) * FF + j0 + 4 * n) = a; *(f32x4*)(EB + ((size_t)u.pm * 2 + fr) * FF + j0 + 4 * n) = b; }
;                         if (ai == 1 && wr == 1 && m == 3 && fr >= 14) { *(f32x4*)(EA + ((size_t)u.pm * 4 + 2 + (fr - 14)) * FF + j0 + 4 * n) = a;
;                             if ((u.pm & 7) == 7) *(f32x4*)(o_conv_p + ((size_t)(u.pm >> 3) * 2 + (fr - 14)) * FF + j0 + 4 * n) = a; }
;                     } else {
;                         const int t = fr & 7, bb = (r - 16384) >> 3;
; #pragma unroll
;                         for (int e2 = 0; e2 < 4; ++e2) { p1[e2] = ror1(a[e2]); p2[e2] = ror2(a[e2]); }
;                         if (t < 2) { const f32x4 h1 = *(const f32x4*)(state_conv + ((size_t)bb * 2 + 1) * FF + j0 + 4 * n);
;                             if (t == 0) { p1 = h1; p2 = *(const f32x4*)(state_conv + ((size_t)bb * 2) * FF + j0 + 4 * n); } else p2 = h1; }
;                         if (t >= 6) *(f32x4*)(o_conv_s + ((size_t)bb * 2 + (t - 6)) * FF + j0 + 4 * n) = a;
;                     }
;                     f32x4 hv;
; #pragma unroll
;                     for (int e2 = 0; e2 < 1; ++e2) {
;                         const f32x4 c4 = cb + w0 * p2 + w1 * p1 + w2 * a;
;                         const f32x4 z = c4 * ((c4 * c4) * (-0.10294324f) + (-2.3022082f));
;                         f32x4 den; den[0] = 1.f + __builtin_amdgcn_exp2f(z[0]); den[1] = 1.f + __builtin_amdgcn_exp2f(z[1]); den[2] = 1.f + __builtin_amdgcn_exp2f(z[2]); den[3] = 1.f + __builtin_amdgcn_exp2f(z[3]);
;                         f32x4 rc; rc[0] = frcp(den[0]); rc[1] = frcp(den[1]); rc[2] = frcp(den[2]); rc[3] = frcp(den[3]);
;                         hv = (c4 * rc) * b; }
.Lepi5_noconvp:
	s_mov_b64 exec, -1
.Lepi5_noedge1:
	v_fma_f32 v208, v74, v250, v226
	v_fma_f32 v209, v75, v251, v227
	v_fma_f32 v210, v76, v252, v228
	v_fma_f32 v211, v77, v253, v229
	v_fmac_f32_dpp v208, v74, v242 row_shr:1 row_mask:0xf bank_mask:0xf
	v_fmac_f32_dpp v209, v75, v243 row_shr:1 row_mask:0xf bank_mask:0xf
	v_fmac_f32_dpp v210, v76, v244 row_shr:1 row_mask:0xf bank_mask:0xf
	v_fmac_f32_dpp v211, v77, v245 row_shr:1 row_mask:0xf bank_mask:0xf
	v_fmac_f32_dpp v208, v74, v234 row_shr:2 row_mask:0xf bank_mask:0xf
	v_fmac_f32_dpp v209, v75, v235 row_shr:2 row_mask:0xf bank_mask:0xf
	v_fmac_f32_dpp v210, v76, v236 row_shr:2 row_mask:0xf bank_mask:0xf
	v_fmac_f32_dpp v211, v77, v237 row_shr:2 row_mask:0xf bank_mask:0xf
	v_fmac_f32_dpp v208, v78, v104 row_ror:1 row_mask:0xf bank_mask:0xf
	v_fmac_f32_dpp v209, v79, v105 row_ror:1 row_mask:0xf bank_mask:0xf
	v_fmac_f32_dpp v210, v80, v106 row_ror:1 row_mask:0xf bank_mask:0xf
	v_fmac_f32_dpp v211, v81, v107 row_ror:1 row_mask:0xf bank_mask:0xf
	v_fmac_f32_dpp v208, v78, v112 row_ror:2 row_mask:0xf bank_mask:0xf
	v_fmac_f32_dpp v209, v79, v113 row_ror:2 row_mask:0xf bank_mask:0xf
	v_fmac_f32_dpp v210, v80, v114 row_ror:2 row_mask:0xf bank_mask:0xf
	v_fmac_f32_dpp v211, v81, v115 row_ror:2 row_mask:0xf bank_mask:0xf
	v_mul_f32_e32 v86, v208, v208
	v_mul_f32_e32 v87, v209, v209
	v_mul_f32_e32 v92, v210, v210
	v_mul_f32_e32 v93, v211, v211
	v_fmamk_f32 v86, v86, 0xbdd2d3e8, v98
	v_fmamk_f32 v87, v87, 0xbdd2d3e8, v98
	v_fmamk_f32 v92, v92, 0xbdd2d3e8, v98
	v_fmamk_f32 v93, v93, 0xbdd2d3e8, v98
	v_mul_f32_e32 v86, v208, v86
	v_mul_f32_e32 v87, v209, v87
	v_mul_f32_e32 v92, v210, v92
	v_mul_f32_e32 v93, v211, v93
	v_exp_f32_e32 v86, v86
	v_exp_f32_e32 v87, v87
	v_exp_f32_e32 v92, v92
	v_exp_f32_e32 v93, v93
	v_mul_f32_e32 v208, v208, v66
	v_mul_f32_e32 v209, v209, v67
	v_mul_f32_e32 v210, v210, v68
	v_mul_f32_e32 v211, v211, v69
	v_add_f32_e32 v86, 1.0, v86
	v_add_f32_e32 v87, 1.0, v87
	v_add_f32_e32 v92, 1.0, v92
	v_add_f32_e32 v93, 1.0, v93
	v_rcp_f32_e32 v86, v86
	v_rcp_f32_e32 v87, v87
	v_rcp_f32_e32 v92, v92
	v_rcp_f32_e32 v93, v93
	s_nop 0
	v_mul_f32_e32 v208, v208, v86
	v_mul_f32_e32 v209, v209, v87
	v_mul_f32_e32 v210, v210, v92
	v_mul_f32_e32 v211, v211, v93
	v_cvt_pk_bf16_f32 v66, v208, v209
	v_cvt_pk_bf16_f32 v67, v210, v211
	v_fma_f32 v208, v6, v204, v230
	v_fma_f32 v209, v7, v205, v231
	v_fma_f32 v210, v8, v206, v232
	v_fma_f32 v211, v9, v207, v233
	v_fmac_f32_dpp v208, v6, v246 row_shr:1 row_mask:0xf bank_mask:0xf
	v_fmac_f32_dpp v209, v7, v247 row_shr:1 row_mask:0xf bank_mask:0xf
	v_fmac_f32_dpp v210, v8, v248 row_shr:1 row_mask:0xf bank_mask:0xf
	v_fmac_f32_dpp v211, v9, v249 row_shr:1 row_mask:0xf bank_mask:0xf
	v_fmac_f32_dpp v208, v6, v238 row_shr:2 row_mask:0xf bank_mask:0xf
	v_fmac_f32_dpp v209, v7, v239 row_shr:2 row_mask:0xf bank_mask:0xf
	v_fmac_f32_dpp v210, v8, v240 row_shr:2 row_mask:0xf bank_mask:0xf
	v_fmac_f32_dpp v211, v9, v241 row_shr:2 row_mask:0xf bank_mask:0xf
	v_fmac_f32_dpp v208, v14, v108 row_ror:1 row_mask:0xf bank_mask:0xf
	v_fmac_f32_dpp v209, v15, v109 row_ror:1 row_mask:0xf bank_mask:0xf
	v_fmac_f32_dpp v210, v16, v110 row_ror:1 row_mask:0xf bank_mask:0xf
	v_fmac_f32_dpp v211, v17, v111 row_ror:1 row_mask:0xf bank_mask:0xf
	v_fmac_f32_dpp v208, v14, v116 row_ror:2 row_mask:0xf bank_mask:0xf
	v_fmac_f32_dpp v209, v15, v117 row_ror:2 row_mask:0xf bank_mask:0xf
	v_fmac_f32_dpp v210, v16, v118 row_ror:2 row_mask:0xf bank_mask:0xf
	v_fmac_f32_dpp v211, v17, v119 row_ror:2 row_mask:0xf bank_mask:0xf
	v_mul_f32_e32 v86, v208, v208
	v_mul_f32_e32 v87, v209, v209
	v_mul_f32_e32 v92, v210, v210
	v_mul_f32_e32 v93, v211, v211
	v_fmamk_f32 v86, v86, 0xbdd2d3e8, v98
	v_fmamk_f32 v87, v87, 0xbdd2d3e8, v98
	v_fmamk_f32 v92, v92, 0xbdd2d3e8, v98
	v_fmamk_f32 v93, v93, 0xbdd2d3e8, v98
	v_mul_f32_e32 v86, v208, v86
	v_mul_f32_e32 v87, v209, v87
	v_mul_f32_e32 v92, v210, v92
	v_mul_f32_e32 v93, v211, v93
	v_exp_f32_e32 v86, v86
	v_exp_f32_e32 v87, v87
	v_exp_f32_e32 v92, v92
	v_exp_f32_e32 v93, v93
	v_mul_f32_e32 v208, v208, v2
	v_mul_f32_e32 v209, v209, v3
	v_mul_f32_e32 v210, v210, v4
	v_mul_f32_e32 v211, v211, v5
	v_add_f32_e32 v86, 1.0, v86
	v_add_f32_e32 v87, 1.0, v87
	v_add_f32_e32 v92, 1.0, v92
	v_add_f32_e32 v93, 1.0, v93
	v_rcp_f32_e32 v86, v86
	v_rcp_f32_e32 v87, v87
	v_rcp_f32_e32 v92, v92
	v_rcp_f32_e32 v93, v93
	s_nop 0
	v_mul_f32_e32 v208, v208, v86
	v_mul_f32_e32 v209, v209, v87
	v_mul_f32_e32 v210, v210, v92
	v_mul_f32_e32 v211, v211, v93
	v_cvt_pk_bf16_f32 v68, v208, v209
	v_cvt_pk_bf16_f32 v69, v210, v211
	global_store_dwordx4 v212, v[66:69], s[80:81]
	s_branch .Lepi5_done
.Lepi5_done:
	v_readlane_b32 s79, v254, 62
	s_andn2_b64 vcc, exec, s[8:9]
	s_mov_b64 s[2:3], -1
.Lepi5_join:
	s_cbranch_vccnz .LBB0_881
	s_andn2_b64 vcc, exec, s[12:13]
	s_cbranch_vccnz .LBB0_880
	s_barrier
	s_branch .LBB0_880
